# diff-attention epilogue: xor-1/2/4/8 row-sum butterfly steps via DPP adds instead of ds_bpermute round trips
# baseline (speedup 1.0000x reference)
; #define SBAR() __builtin_amdgcn_sched_barrier(0)
; template <bool DIFF> ...
;     ...
;       BIAS_APPLY(t, 1, a1, b1, cb1);
;       { const float x1 = fmaf(cb1, C, e1), x2 = fmaf(cb1, C, e2);
; #pragma unroll
;       for (int r = 0; r < 16; ++r) a1[r] = __builtin_amdgcn_exp2f(fmaf(a1[r], C, x1));
;       if (DIFF) {
; #pragma unroll
;         for (int r = 0; r < 16; ++r) a1[r] = fmaf(nsg, __builtin_amdgcn_exp2f(fmaf(b1[r], C, x2)), a1[r]);
;       } }
;       PK4(a1, 0, pa2); PK4(a1, 8, pa3);
;       SBAR();
;       pv_step<2>(o, vb0, pa2); pv_step<3>(o, vb0, pa3);
;     ...
;     for (int d = 0; d < 4; ++d) gsub[d] = subg[32 * d + r32] * 0.8f;
; #pragma unroll
;     for (int r = 0; r < 16; ++r) {
;       float ss = o[0][r] * o[0][r] + o[1][r] * o[1][r] + o[2][r] * o[2][r] + o[3][r] * o[3][r];
;       ss += __shfl_xor(ss, 1); ss += __shfl_xor(ss, 2); ss += __shfl_xor(ss, 4); ss += __shfl_xor(ss, 8); ss += __shfl_xor(ss, 16);
.LBB0_260:
	s_or_b64 exec, exec, s[4:5]
	s_waitcnt lgkmcnt(0)
	v_fmac_f32_e32 v188, 0x3e38aa3b, v96
	v_fmac_f32_e32 v187, 0x3e38aa3b, v96
	v_fmamk_f32 v80, v80, 0x3e38aa3b, v188
	v_fmamk_f32 v81, v81, 0x3e38aa3b, v188
	v_fmamk_f32 v82, v82, 0x3e38aa3b, v188
	v_fmamk_f32 v83, v83, 0x3e38aa3b, v188
	v_fmamk_f32 v84, v84, 0x3e38aa3b, v188
	v_fmamk_f32 v85, v85, 0x3e38aa3b, v188
	v_fmamk_f32 v86, v86, 0x3e38aa3b, v188
	v_fmamk_f32 v87, v87, 0x3e38aa3b, v188
	v_fmamk_f32 v88, v88, 0x3e38aa3b, v188
	v_fmamk_f32 v89, v89, 0x3e38aa3b, v188
	v_fmamk_f32 v90, v90, 0x3e38aa3b, v188
	v_fmamk_f32 v91, v91, 0x3e38aa3b, v188
	v_fmamk_f32 v92, v92, 0x3e38aa3b, v188
	v_fmamk_f32 v93, v93, 0x3e38aa3b, v188
	v_fmamk_f32 v94, v94, 0x3e38aa3b, v188
	v_fmac_f32_e32 v188, 0x3e38aa3b, v95
	v_fmamk_f32 v64, v64, 0x3e38aa3b, v187
	v_fmamk_f32 v65, v65, 0x3e38aa3b, v187
	v_fmamk_f32 v66, v66, 0x3e38aa3b, v187
	v_fmamk_f32 v67, v67, 0x3e38aa3b, v187
	v_fmamk_f32 v68, v68, 0x3e38aa3b, v187
	v_fmamk_f32 v69, v69, 0x3e38aa3b, v187
	v_fmamk_f32 v70, v70, 0x3e38aa3b, v187
	v_fmamk_f32 v71, v71, 0x3e38aa3b, v187
	v_fmamk_f32 v72, v72, 0x3e38aa3b, v187
	v_fmamk_f32 v73, v73, 0x3e38aa3b, v187
	v_fmamk_f32 v74, v74, 0x3e38aa3b, v187
	v_fmamk_f32 v75, v75, 0x3e38aa3b, v187
	v_fmamk_f32 v76, v76, 0x3e38aa3b, v187
	v_fmamk_f32 v77, v77, 0x3e38aa3b, v187
	v_fmamk_f32 v78, v78, 0x3e38aa3b, v187
	v_fmac_f32_e32 v187, 0x3e38aa3b, v79
	v_exp_f32_e32 v80, v80
	v_exp_f32_e32 v81, v81
	v_exp_f32_e32 v82, v82
	v_exp_f32_e32 v83, v83
	v_exp_f32_e32 v84, v84
	v_exp_f32_e32 v85, v85
	v_exp_f32_e32 v86, v86
	v_exp_f32_e32 v87, v87
	v_exp_f32_e32 v88, v88
	v_exp_f32_e32 v89, v89
	v_exp_f32_e32 v90, v90
	v_exp_f32_e32 v91, v91
	v_exp_f32_e32 v92, v92
	v_exp_f32_e32 v93, v93
	v_exp_f32_e32 v94, v94
	v_exp_f32_e32 v95, v188
	v_exp_f32_e32 v64, v64
	v_exp_f32_e32 v65, v65
	v_exp_f32_e32 v66, v66
	v_exp_f32_e32 v67, v67
	v_exp_f32_e32 v68, v68
	v_exp_f32_e32 v69, v69
	v_exp_f32_e32 v70, v70
	v_exp_f32_e32 v71, v71
	v_exp_f32_e32 v72, v72
	v_exp_f32_e32 v73, v73
	v_exp_f32_e32 v74, v74
	v_exp_f32_e32 v75, v75
	v_exp_f32_e32 v76, v76
	v_exp_f32_e32 v77, v77
	v_exp_f32_e32 v78, v78
	v_exp_f32_e32 v79, v187
	s_lshl_b64 s[4:5], s[30:31], 12
	s_add_u32 s2, s42, s4
	s_addc_u32 s5, s43, s5
	v_pk_fma_f32 v[64:65], v[144:145], v[64:65], v[80:81]
	v_pk_fma_f32 v[66:67], v[144:145], v[66:67], v[82:83]
	v_pk_fma_f32 v[68:69], v[144:145], v[68:69], v[84:85]
	v_pk_fma_f32 v[70:71], v[144:145], v[70:71], v[86:87]
	v_pk_fma_f32 v[72:73], v[144:145], v[72:73], v[88:89]
	v_pk_fma_f32 v[74:75], v[144:145], v[74:75], v[90:91]
	v_pk_fma_f32 v[76:77], v[144:145], v[76:77], v[92:93]
	v_pk_fma_f32 v[78:79], v[144:145], v[78:79], v[94:95]
	s_add_u32 s4, s2, s38
	v_cvt_pk_bf16_f32 v64, v64, v65
	v_cvt_pk_bf16_f32 v65, v66, v67
	v_cvt_pk_bf16_f32 v66, v68, v69
	v_cvt_pk_bf16_f32 v67, v70, v71
	v_cvt_pk_bf16_f32 v68, v72, v73
	v_cvt_pk_bf16_f32 v69, v74, v75
	v_cvt_pk_bf16_f32 v70, v76, v77
	v_cvt_pk_bf16_f32 v71, v78, v79
	s_addc_u32 s5, s5, 0
	v_permlane32_swap_b32_e32 v64, v66
	v_permlane32_swap_b32_e32 v65, v67
	v_permlane32_swap_b32_e32 v68, v70
	v_permlane32_swap_b32_e32 v69, v71
	ds_read_b64_tr_b16 v[72:73], v146 offset:0x2000
	ds_read_b64_tr_b16 v[74:75], v146 offset:0x2800
	ds_read_b64_tr_b16 v[76:77], v146 offset:0x2200
	ds_read_b64_tr_b16 v[78:79], v146 offset:0x2a00
	ds_read_b64_tr_b16 v[80:81], v146 offset:0x2400
	ds_read_b64_tr_b16 v[82:83], v146 offset:0x2c00
	ds_read_b64_tr_b16 v[84:85], v146 offset:0x2600
	ds_read_b64_tr_b16 v[86:87], v146 offset:0x2e00
	s_waitcnt lgkmcnt(0)
	s_nop 0
	v_mfma_f32_32x32x16_bf16 v[0:15], v[64:67], v[72:75], v[0:15]
	ds_read_b64_tr_b16 v[72:73], v146 offset:0x3000
	ds_read_b64_tr_b16 v[74:75], v146 offset:0x3800
	v_mfma_f32_32x32x16_bf16 v[16:31], v[64:67], v[76:79], v[16:31]
	ds_read_b64_tr_b16 v[76:77], v146 offset:0x3200
	ds_read_b64_tr_b16 v[78:79], v146 offset:0x3a00
	v_mfma_f32_32x32x16_bf16 v[32:47], v[64:67], v[80:83], v[32:47]
	ds_read_b64_tr_b16 v[80:81], v146 offset:0x3400
	ds_read_b64_tr_b16 v[82:83], v146 offset:0x3c00
	ds_read_b64_tr_b16 v[88:89], v146 offset:0x3600
	ds_read_b64_tr_b16 v[90:91], v146 offset:0x3e00
	s_waitcnt lgkmcnt(0)
	v_mfma_f32_32x32x16_bf16 v[48:63], v[64:67], v[84:87], v[48:63]
	v_lshlrev_b32_e32 v64, 2, v164
	v_mfma_f32_32x32x16_bf16 v[0:15], v[68:71], v[72:75], v[0:15]
	global_load_dword v72, v64, s[28:29]
	global_load_dword v73, v64, s[28:29] offset:128
	global_load_dword v74, v64, s[28:29] offset:256
	global_load_dword v75, v64, s[28:29] offset:384
	v_ashrrev_i32_e32 v149, 31, v148
	v_lshlrev_b32_e32 v146, 1, v164
	v_mfma_f32_32x32x16_bf16 v[16:31], v[68:71], v[76:79], v[16:31]
	v_mfma_f32_32x32x16_bf16 v[32:47], v[68:71], v[80:83], v[32:47]
	s_nop 10
	v_mul_f32_e32 v64, v16, v16
	v_fmac_f32_e32 v64, v0, v0
	v_mfma_f32_32x32x16_bf16 v[48:63], v[68:71], v[88:91], v[48:63]
	v_fmac_f32_e32 v64, v32, v32
	s_nop 10
	v_fmac_f32_e32 v64, v48, v48

; template <bool DIFF> ...
;     ...
;       ss += __shfl_xor(ss, 1); ss += __shfl_xor(ss, 2); ss += __shfl_xor(ss, 4); ss += __shfl_xor(ss, 8); ss += __shfl_xor(ss, 16);
	s_waitcnt lgkmcnt(0)
	s_nop 1
	v_add_f32_dpp v64, v64, v64 quad_perm:[1,0,3,2] row_mask:0xf bank_mask:0xf

; template <bool DIFF> ...
;     ...
;       ss += __shfl_xor(ss, 1); ss += __shfl_xor(ss, 2); ss += __shfl_xor(ss, 4); ss += __shfl_xor(ss, 8); ss += __shfl_xor(ss, 16);
	s_waitcnt lgkmcnt(0)
	s_nop 1
	v_add_f32_dpp v64, v64, v64 quad_perm:[2,3,0,1] row_mask:0xf bank_mask:0xf

; template <bool DIFF> ...
;     ...
;       ss += __shfl_xor(ss, 1); ss += __shfl_xor(ss, 2); ss += __shfl_xor(ss, 4); ss += __shfl_xor(ss, 8); ss += __shfl_xor(ss, 16);
	s_waitcnt lgkmcnt(0)
	s_nop 1
	v_add_f32_dpp v64, v64, v64 row_half_mirror row_mask:0xf bank_mask:0xf

; __device__ __forceinline__ int crow(int r, int hi) { return (r & 3) + 8 * (r >> 2) + 4 * hi; }
; __device__ __forceinline__ unsigned short f2bf(float f) { unsigned u = __float_as_uint(f); return (unsigned short)((u + 0x7fffu + ((u >> 16) & 1u)) >> 16); }
; __device__ __forceinline__ unsigned f2bf(float f) { unsigned u = __float_as_uint(f); return (u + 0x7fffu + ((u >> 16) & 1u)) >> 16; }
; template <bool DIFF> ...
;     ...
;       float ss = o[0][r] * o[0][r] + o[1][r] * o[1][r] + o[2][r] * o[2][r] + o[3][r] * o[3][r];
;       ss += __shfl_xor(ss, 1); ss += __shfl_xor(ss, 2); ss += __shfl_xor(ss, 4); ss += __shfl_xor(ss, 8); ss += __shfl_xor(ss, 16);
;       const float rs = 1.0f / sqrtf(ss * (1.0f / 128.0f) + 1e-6f);
;       bf16* orow = Ow + (size_t)crow(r, hi) * 2048 + r32;
; #pragma unroll
;       for (int d = 0; d < 4; ++d) orow[32 * d] = f2bf(o[d][r] * rs * gsub[d]);
	s_waitcnt lgkmcnt(0)
	s_nop 1
	v_add_f32_dpp v66, v64, v64 row_mirror row_mask:0xf bank_mask:0xf
	ds_bpermute_b32 v67, v158, v66
	v_lshlrev_b32_e32 v64, 14, v165
	v_mov_b32_e32 v65, v147
	s_waitcnt lgkmcnt(0)
	v_add_f32_e32 v66, v66, v67
	v_fmamk_f32 v66, v66, 0x3c000000, v160
	v_mul_f32_e32 v67, 0x4f800000, v66
	v_cmp_gt_f32_e32 vcc, s74, v66
	s_nop 1
	v_cndmask_b32_e32 v68, v66, v67, vcc
	v_sqrt_f32_e32 v69, v68
	v_lshlrev_b64 v[66:67], 12, v[148:149]
	v_lshl_add_u64 v[66:67], s[4:5], 0, v[66:67]
	v_lshl_add_u64 v[66:67], v[66:67], 0, v[146:147]
	v_add_u32_e32 v70, -1, v69
	v_add_u32_e32 v71, 1, v69
	v_fma_f32 v76, -v70, v69, v68
	v_fma_f32 v77, -v71, v69, v68
	v_cmp_ge_f32_e64 s[4:5], 0, v76
	v_lshl_add_u64 v[64:65], v[66:67], 0, v[64:65]
	s_nop 0
	v_cndmask_b32_e64 v69, v69, v70, s[4:5]
	v_cmp_lt_f32_e64 s[4:5], 0, v77
	s_nop 1
	v_cndmask_b32_e64 v69, v69, v71, s[4:5]
	v_mul_f32_e32 v70, 0x37800000, v69
	v_cndmask_b32_e32 v69, v69, v70, vcc
	v_cmp_class_f32_e32 vcc, v68, v161
	s_nop 1
	v_cndmask_b32_e32 v68, v69, v68, vcc
	v_div_scale_f32 v69, s[4:5], v68, v68, 1.0
	v_rcp_f32_e32 v70, v69
	v_div_scale_f32 v66, vcc, 1.0, v68, 1.0
	v_fma_f32 v67, -v69, v70, 1.0
	v_fmac_f32_e32 v70, v67, v70
	v_mul_f32_e32 v67, v66, v70
	v_fma_f32 v71, -v69, v67, v66
	v_fmac_f32_e32 v67, v71, v70
	v_fma_f32 v66, -v69, v67, v66
	v_div_fmas_f32 v66, v66, v70, v67
	v_div_fixup_f32 v66, v66, v68, 1.0
	v_mul_f32_e32 v67, v0, v66
	s_waitcnt vmcnt(3)
	v_mul_f32_e32 v0, 0x3f4ccccd, v72
	v_mul_f32_e32 v68, v16, v66
	v_mul_f32_e32 v69, v32, v66
	v_mul_f32_e32 v66, v48, v66
	s_waitcnt vmcnt(2)
	v_mul_f32_e32 v16, 0x3f4ccccd, v73
	s_waitcnt vmcnt(1)
	v_mul_f32_e32 v32, 0x3f4ccccd, v74
	s_waitcnt vmcnt(0)
	v_mul_f32_e32 v48, 0x3f4ccccd, v75
	v_mul_f32_e32 v67, v0, v67
	v_mul_f32_e32 v68, v16, v68
	v_mul_f32_e32 v69, v32, v69
	v_mul_f32_e32 v66, v48, v66
	v_bfe_u32 v70, v67, 16, 1
	v_bfe_u32 v71, v68, 16, 1
	v_bfe_u32 v72, v69, 16, 1
	v_bfe_u32 v73, v66, 16, 1
	v_add3_u32 v67, v67, v70, s75
	v_add3_u32 v68, v68, v71, s75
	v_add3_u32 v69, v69, v72, s75
	v_add3_u32 v66, v66, v73, s75
	global_store_short_d16_hi v[64:65], v67, off
	global_store_short_d16_hi v[64:65], v68, off offset:64
	global_store_short_d16_hi v[64:65], v69, off offset:128
	global_store_short_d16_hi v[64:65], v66, off offset:192
	v_mul_f32_e32 v66, v17, v17
	v_fmac_f32_e32 v66, v1, v1
	v_fmac_f32_e32 v66, v33, v33
	v_fmac_f32_e32 v66, v49, v49

; template <bool DIFF> ...
;     ...
;       ss += __shfl_xor(ss, 1); ss += __shfl_xor(ss, 2); ss += __shfl_xor(ss, 4); ss += __shfl_xor(ss, 8); ss += __shfl_xor(ss, 16);
	s_waitcnt lgkmcnt(0)
	s_nop 1
	v_add_f32_dpp v66, v66, v66 quad_perm:[1,0,3,2] row_mask:0xf bank_mask:0xf

; template <bool DIFF> ...
;     ...
;       ss += __shfl_xor(ss, 1); ss += __shfl_xor(ss, 2); ss += __shfl_xor(ss, 4); ss += __shfl_xor(ss, 8); ss += __shfl_xor(ss, 16);
	s_waitcnt lgkmcnt(0)
	s_nop 1
	v_add_f32_dpp v66, v66, v66 quad_perm:[2,3,0,1] row_mask:0xf bank_mask:0xf

; template <bool DIFF> ...
;     ...
;       ss += __shfl_xor(ss, 1); ss += __shfl_xor(ss, 2); ss += __shfl_xor(ss, 4); ss += __shfl_xor(ss, 8); ss += __shfl_xor(ss, 16);
	s_waitcnt lgkmcnt(0)
	s_nop 1
	v_add_f32_dpp v66, v66, v66 row_half_mirror row_mask:0xf bank_mask:0xf

; __device__ __forceinline__ int crow(int r, int hi) { return (r & 3) + 8 * (r >> 2) + 4 * hi; }
; __device__ __forceinline__ unsigned short f2bf(float f) { unsigned u = __float_as_uint(f); return (unsigned short)((u + 0x7fffu + ((u >> 16) & 1u)) >> 16); }
; __device__ __forceinline__ unsigned f2bf(float f) { unsigned u = __float_as_uint(f); return (u + 0x7fffu + ((u >> 16) & 1u)) >> 16; }
; template <bool DIFF> ...
;     ...
;       float ss = o[0][r] * o[0][r] + o[1][r] * o[1][r] + o[2][r] * o[2][r] + o[3][r] * o[3][r];
;       ss += __shfl_xor(ss, 1); ss += __shfl_xor(ss, 2); ss += __shfl_xor(ss, 4); ss += __shfl_xor(ss, 8); ss += __shfl_xor(ss, 16);
;       const float rs = 1.0f / sqrtf(ss * (1.0f / 128.0f) + 1e-6f);
;       bf16* orow = Ow + (size_t)crow(r, hi) * 2048 + r32;
; #pragma unroll
;       for (int d = 0; d < 4; ++d) orow[32 * d] = f2bf(o[d][r] * rs * gsub[d]);
	s_waitcnt lgkmcnt(0)
	s_nop 1
	v_add_f32_dpp v66, v66, v66 row_mirror row_mask:0xf bank_mask:0xf
	ds_bpermute_b32 v67, v158, v66
	s_waitcnt lgkmcnt(0)
	v_add_f32_e32 v66, v66, v67
	v_fmamk_f32 v66, v66, 0x3c000000, v160
	v_mul_f32_e32 v67, 0x4f800000, v66
	v_cmp_gt_f32_e32 vcc, s74, v66
	s_nop 1
	v_cndmask_b32_e32 v68, v66, v67, vcc
	v_sqrt_f32_e32 v69, v68
	v_add_co_u32_e64 v66, s[4:5], s59, v64
	v_add_u32_e32 v70, -1, v69
	s_nop 0
	v_addc_co_u32_e64 v67, s[4:5], 0, v65, s[4:5]
	v_add_u32_e32 v71, 1, v69
	v_fma_f32 v72, -v70, v69, v68
	v_fma_f32 v73, -v71, v69, v68
	v_cmp_ge_f32_e64 s[4:5], 0, v72
	s_nop 1
	v_cndmask_b32_e64 v69, v69, v70, s[4:5]
	v_cmp_lt_f32_e64 s[4:5], 0, v73
	s_nop 1
	v_cndmask_b32_e64 v69, v69, v71, s[4:5]
	v_mul_f32_e32 v70, 0x37800000, v69
	v_cndmask_b32_e32 v69, v69, v70, vcc
	v_cmp_class_f32_e32 vcc, v68, v161
	s_nop 1
	v_cndmask_b32_e32 v70, v69, v68, vcc
	v_div_scale_f32 v71, s[4:5], v70, v70, 1.0
	v_rcp_f32_e32 v72, v71
	v_add_co_u32_e32 v68, vcc, s76, v64
	v_fma_f32 v74, -v71, v72, 1.0
	s_nop 0
	v_addc_co_u32_e32 v69, vcc, 0, v65, vcc
	v_div_scale_f32 v73, vcc, 1.0, v70, 1.0
	v_fmac_f32_e32 v72, v74, v72
	v_mul_f32_e32 v74, v73, v72
	v_fma_f32 v75, -v71, v74, v73
	v_fmac_f32_e32 v74, v75, v72
	v_fma_f32 v71, -v71, v74, v73
	v_div_fmas_f32 v71, v71, v72, v74
	v_div_fixup_f32 v70, v71, v70, 1.0
	v_mul_f32_e32 v1, v1, v70
	v_mul_f32_e32 v17, v17, v70
	v_mul_f32_e32 v33, v33, v70
	v_mul_f32_e32 v1, v0, v1
	v_mul_f32_e32 v17, v16, v17
	v_mul_f32_e32 v33, v32, v33
	v_bfe_u32 v71, v1, 16, 1
	v_bfe_u32 v72, v17, 16, 1
	v_bfe_u32 v73, v33, 16, 1
	v_add3_u32 v1, v1, v71, s75
	v_add3_u32 v17, v17, v72, s75
	global_store_short_d16_hi v[68:69], v1, off offset:-4096
	global_store_short_d16_hi v[66:67], v17, off offset:64
	v_add3_u32 v1, v33, v73, s75
	global_store_short_d16_hi v[66:67], v1, off offset:128
	v_mul_f32_e32 v1, v49, v70
	v_mul_f32_e32 v1, v48, v1
	v_bfe_u32 v17, v1, 16, 1
	v_add3_u32 v1, v1, v17, s75
	global_store_short_d16_hi v[66:67], v1, off offset:192
	v_mul_f32_e32 v1, v18, v18
	v_fmac_f32_e32 v1, v2, v2
	v_fmac_f32_e32 v1, v34, v34
	v_fmac_f32_e32 v1, v50, v50

; template <bool DIFF> ...
;     ...
;       ss += __shfl_xor(ss, 1); ss += __shfl_xor(ss, 2); ss += __shfl_xor(ss, 4); ss += __shfl_xor(ss, 8); ss += __shfl_xor(ss, 16);
	s_waitcnt lgkmcnt(0)
	s_nop 1
	v_add_f32_dpp v1, v1, v1 quad_perm:[1,0,3,2] row_mask:0xf bank_mask:0xf

; template <bool DIFF> ...
;     ...
;       ss += __shfl_xor(ss, 1); ss += __shfl_xor(ss, 2); ss += __shfl_xor(ss, 4); ss += __shfl_xor(ss, 8); ss += __shfl_xor(ss, 16);
	s_waitcnt lgkmcnt(0)
	s_nop 1
	v_add_f32_dpp v1, v1, v1 quad_perm:[2,3,0,1] row_mask:0xf bank_mask:0xf

; template <bool DIFF> ...
;     ...
;       ss += __shfl_xor(ss, 1); ss += __shfl_xor(ss, 2); ss += __shfl_xor(ss, 4); ss += __shfl_xor(ss, 8); ss += __shfl_xor(ss, 16);
	s_waitcnt lgkmcnt(0)
	s_nop 1
	v_add_f32_dpp v1, v1, v1 row_half_mirror row_mask:0xf bank_mask:0xf

; __device__ __forceinline__ int crow(int r, int hi) { return (r & 3) + 8 * (r >> 2) + 4 * hi; }
; __device__ __forceinline__ unsigned short f2bf(float f) { unsigned u = __float_as_uint(f); return (unsigned short)((u + 0x7fffu + ((u >> 16) & 1u)) >> 16); }
; __device__ __forceinline__ unsigned f2bf(float f) { unsigned u = __float_as_uint(f); return (u + 0x7fffu + ((u >> 16) & 1u)) >> 16; }
; template <bool DIFF> ...
;     ...
;       float ss = o[0][r] * o[0][r] + o[1][r] * o[1][r] + o[2][r] * o[2][r] + o[3][r] * o[3][r];
;       ss += __shfl_xor(ss, 1); ss += __shfl_xor(ss, 2); ss += __shfl_xor(ss, 4); ss += __shfl_xor(ss, 8); ss += __shfl_xor(ss, 16);
;       const float rs = 1.0f / sqrtf(ss * (1.0f / 128.0f) + 1e-6f);
;       bf16* orow = Ow + (size_t)crow(r, hi) * 2048 + r32;
; #pragma unroll
;       for (int d = 0; d < 4; ++d) orow[32 * d] = f2bf(o[d][r] * rs * gsub[d]);
	s_waitcnt lgkmcnt(0)
	s_nop 1
	v_add_f32_dpp v1, v1, v1 row_mirror row_mask:0xf bank_mask:0xf
	ds_bpermute_b32 v17, v158, v1
	s_waitcnt lgkmcnt(0)
	v_add_f32_e32 v1, v1, v17
	v_fmamk_f32 v1, v1, 0x3c000000, v160
	v_mul_f32_e32 v17, 0x4f800000, v1
	v_cmp_gt_f32_e32 vcc, s74, v1
	s_nop 1
	v_cndmask_b32_e32 v1, v1, v17, vcc
	v_sqrt_f32_e32 v17, v1
	s_nop 0
	v_add_u32_e32 v33, -1, v17
	v_add_u32_e32 v49, 1, v17
	v_fma_f32 v66, -v33, v17, v1
	v_fma_f32 v67, -v49, v17, v1
	v_cmp_ge_f32_e64 s[4:5], 0, v66
	s_nop 1
	v_cndmask_b32_e64 v17, v17, v33, s[4:5]
	v_cmp_lt_f32_e64 s[4:5], 0, v67
	s_nop 1
	v_cndmask_b32_e64 v17, v17, v49, s[4:5]
	v_mul_f32_e32 v33, 0x37800000, v17
	v_cndmask_b32_e32 v17, v17, v33, vcc
	v_cmp_class_f32_e32 vcc, v1, v161
	s_nop 1
	v_cndmask_b32_e32 v1, v17, v1, vcc
	v_div_scale_f32 v17, s[4:5], v1, v1, 1.0
	v_rcp_f32_e32 v33, v17
	v_div_scale_f32 v49, vcc, 1.0, v1, 1.0
	v_fma_f32 v66, -v17, v33, 1.0
	v_fmac_f32_e32 v33, v66, v33
	v_mul_f32_e32 v66, v49, v33
	v_fma_f32 v67, -v17, v66, v49
	v_fmac_f32_e32 v66, v67, v33
	v_fma_f32 v17, -v17, v66, v49
	v_div_fmas_f32 v17, v17, v33, v66
	v_div_fixup_f32 v1, v17, v1, 1.0
	v_mul_f32_e32 v2, v2, v1
	v_mul_f32_e32 v17, v18, v1
	v_mul_f32_e32 v18, v34, v1
	v_mul_f32_e32 v1, v50, v1
	v_mul_f32_e32 v2, v0, v2
	v_mul_f32_e32 v17, v16, v17
	v_mul_f32_e32 v18, v32, v18
	v_mul_f32_e32 v1, v48, v1
	v_bfe_u32 v33, v2, 16, 1
	v_bfe_u32 v34, v17, 16, 1
	v_bfe_u32 v49, v18, 16, 1
	v_bfe_u32 v50, v1, 16, 1
	v_add3_u32 v2, v2, v33, s75
	v_add3_u32 v17, v17, v34, s75
	v_add3_u32 v18, v18, v49, s75
	v_add3_u32 v1, v1, v50, s75
	global_store_short_d16_hi v[68:69], v2, off
	global_store_short_d16_hi v[68:69], v17, off offset:64
	global_store_short_d16_hi v[68:69], v18, off offset:128
	global_store_short_d16_hi v[68:69], v1, off offset:192
	v_mul_f32_e32 v1, v19, v19
	v_fmac_f32_e32 v1, v3, v3
	v_fmac_f32_e32 v1, v35, v35
	v_fmac_f32_e32 v1, v51, v51

; template <bool DIFF> ...
;     ...
;       ss += __shfl_xor(ss, 1); ss += __shfl_xor(ss, 2); ss += __shfl_xor(ss, 4); ss += __shfl_xor(ss, 8); ss += __shfl_xor(ss, 16);
	s_waitcnt lgkmcnt(0)
	s_nop 1
	v_add_f32_dpp v1, v1, v1 quad_perm:[1,0,3,2] row_mask:0xf bank_mask:0xf

; template <bool DIFF> ...
;     ...
;       ss += __shfl_xor(ss, 1); ss += __shfl_xor(ss, 2); ss += __shfl_xor(ss, 4); ss += __shfl_xor(ss, 8); ss += __shfl_xor(ss, 16);
	s_waitcnt lgkmcnt(0)
	s_nop 1
	v_add_f32_dpp v1, v1, v1 quad_perm:[2,3,0,1] row_mask:0xf bank_mask:0xf

; template <bool DIFF> ...
;     ...
;       ss += __shfl_xor(ss, 1); ss += __shfl_xor(ss, 2); ss += __shfl_xor(ss, 4); ss += __shfl_xor(ss, 8); ss += __shfl_xor(ss, 16);
	s_waitcnt lgkmcnt(0)
	s_nop 1
	v_add_f32_dpp v1, v1, v1 row_half_mirror row_mask:0xf bank_mask:0xf

; __device__ __forceinline__ int crow(int r, int hi) { return (r & 3) + 8 * (r >> 2) + 4 * hi; }
; __device__ __forceinline__ unsigned short f2bf(float f) { unsigned u = __float_as_uint(f); return (unsigned short)((u + 0x7fffu + ((u >> 16) & 1u)) >> 16); }
; __device__ __forceinline__ unsigned f2bf(float f) { unsigned u = __float_as_uint(f); return (u + 0x7fffu + ((u >> 16) & 1u)) >> 16; }
; template <bool DIFF> ...
;     ...
;       float ss = o[0][r] * o[0][r] + o[1][r] * o[1][r] + o[2][r] * o[2][r] + o[3][r] * o[3][r];
;       ss += __shfl_xor(ss, 1); ss += __shfl_xor(ss, 2); ss += __shfl_xor(ss, 4); ss += __shfl_xor(ss, 8); ss += __shfl_xor(ss, 16);
;       const float rs = 1.0f / sqrtf(ss * (1.0f / 128.0f) + 1e-6f);
;       bf16* orow = Ow + (size_t)crow(r, hi) * 2048 + r32;
; #pragma unroll
;       for (int d = 0; d < 4; ++d) orow[32 * d] = f2bf(o[d][r] * rs * gsub[d]);
	s_waitcnt lgkmcnt(0)
	s_nop 1
	v_add_f32_dpp v1, v1, v1 row_mirror row_mask:0xf bank_mask:0xf
	ds_bpermute_b32 v2, v158, v1
	s_waitcnt lgkmcnt(0)
	v_add_f32_e32 v1, v1, v2
	v_fmamk_f32 v1, v1, 0x3c000000, v160
	v_mul_f32_e32 v2, 0x4f800000, v1
	v_cmp_gt_f32_e32 vcc, s74, v1
	s_nop 1
	v_cndmask_b32_e32 v1, v1, v2, vcc
	v_sqrt_f32_e32 v2, v1
	s_nop 0
	v_add_u32_e32 v17, -1, v2
	v_add_u32_e32 v18, 1, v2
	v_fma_f32 v33, -v17, v2, v1
	v_fma_f32 v34, -v18, v2, v1
	v_cmp_ge_f32_e64 s[4:5], 0, v33
	s_nop 1
	v_cndmask_b32_e64 v2, v2, v17, s[4:5]
	v_cmp_lt_f32_e64 s[4:5], 0, v34
	s_nop 1
	v_cndmask_b32_e64 v2, v2, v18, s[4:5]
	v_mul_f32_e32 v17, 0x37800000, v2
	v_cndmask_b32_e32 v2, v2, v17, vcc
	v_cmp_class_f32_e32 vcc, v1, v161
	s_nop 1
	v_cndmask_b32_e32 v1, v2, v1, vcc
	v_div_scale_f32 v2, s[4:5], v1, v1, 1.0
	v_rcp_f32_e32 v17, v2
	v_add_co_u32_e32 v66, vcc, s77, v64
	v_fma_f32 v33, -v2, v17, 1.0
	s_nop 0
	v_addc_co_u32_e32 v67, vcc, 0, v65, vcc
	v_div_scale_f32 v18, vcc, 1.0, v1, 1.0
	v_fmac_f32_e32 v17, v33, v17
	v_mul_f32_e32 v33, v18, v17
	v_fma_f32 v34, -v2, v33, v18
	v_fmac_f32_e32 v33, v34, v17
	v_fma_f32 v2, -v2, v33, v18
	v_div_fmas_f32 v2, v2, v17, v33
	v_div_fixup_f32 v1, v2, v1, 1.0
	v_mul_f32_e32 v2, v3, v1
	v_mul_f32_e32 v3, v19, v1
	v_mul_f32_e32 v17, v35, v1
	v_mul_f32_e32 v2, v0, v2
	v_mul_f32_e32 v1, v51, v1
	v_mul_f32_e32 v3, v16, v3
	v_mul_f32_e32 v17, v32, v17
	v_bfe_u32 v18, v2, 16, 1
	v_mul_f32_e32 v1, v48, v1
	v_bfe_u32 v19, v3, 16, 1
	v_bfe_u32 v33, v17, 16, 1
	v_add3_u32 v2, v2, v18, s75
	v_add3_u32 v3, v3, v19, s75
	v_add3_u32 v17, v17, v33, s75
	global_store_short_d16_hi v[66:67], v2, off
	global_store_short_d16_hi v[66:67], v3, off offset:64
	global_store_short_d16_hi v[66:67], v17, off offset:128
	v_bfe_u32 v2, v1, 16, 1
	v_add3_u32 v1, v1, v2, s75
	global_store_short_d16_hi v[66:67], v1, off offset:192
	v_mul_f32_e32 v1, v20, v20
	v_fmac_f32_e32 v1, v4, v4
	v_fmac_f32_e32 v1, v36, v36
	v_fmac_f32_e32 v1, v52, v52

; template <bool DIFF> ...
;     ...
;       ss += __shfl_xor(ss, 1); ss += __shfl_xor(ss, 2); ss += __shfl_xor(ss, 4); ss += __shfl_xor(ss, 8); ss += __shfl_xor(ss, 16);
	s_waitcnt lgkmcnt(0)
	s_nop 1
	v_add_f32_dpp v1, v1, v1 quad_perm:[1,0,3,2] row_mask:0xf bank_mask:0xf

; template <bool DIFF> ...
;     ...
;       ss += __shfl_xor(ss, 1); ss += __shfl_xor(ss, 2); ss += __shfl_xor(ss, 4); ss += __shfl_xor(ss, 8); ss += __shfl_xor(ss, 16);
	s_waitcnt lgkmcnt(0)
	s_nop 1
	v_add_f32_dpp v1, v1, v1 quad_perm:[2,3,0,1] row_mask:0xf bank_mask:0xf

; template <bool DIFF> ...
;     ...
;       ss += __shfl_xor(ss, 1); ss += __shfl_xor(ss, 2); ss += __shfl_xor(ss, 4); ss += __shfl_xor(ss, 8); ss += __shfl_xor(ss, 16);
	s_waitcnt lgkmcnt(0)
	s_nop 1
	v_add_f32_dpp v1, v1, v1 row_half_mirror row_mask:0xf bank_mask:0xf

; __device__ __forceinline__ int crow(int r, int hi) { return (r & 3) + 8 * (r >> 2) + 4 * hi; }
; __device__ __forceinline__ unsigned short f2bf(float f) { unsigned u = __float_as_uint(f); return (unsigned short)((u + 0x7fffu + ((u >> 16) & 1u)) >> 16); }
; __device__ __forceinline__ unsigned f2bf(float f) { unsigned u = __float_as_uint(f); return (u + 0x7fffu + ((u >> 16) & 1u)) >> 16; }
; template <bool DIFF> ...
;     ...
;       float ss = o[0][r] * o[0][r] + o[1][r] * o[1][r] + o[2][r] * o[2][r] + o[3][r] * o[3][r];
;       ss += __shfl_xor(ss, 1); ss += __shfl_xor(ss, 2); ss += __shfl_xor(ss, 4); ss += __shfl_xor(ss, 8); ss += __shfl_xor(ss, 16);
;       const float rs = 1.0f / sqrtf(ss * (1.0f / 128.0f) + 1e-6f);
;       bf16* orow = Ow + (size_t)crow(r, hi) * 2048 + r32;
; #pragma unroll
;       for (int d = 0; d < 4; ++d) orow[32 * d] = f2bf(o[d][r] * rs * gsub[d]);
	s_waitcnt lgkmcnt(0)
	s_nop 1
	v_add_f32_dpp v1, v1, v1 row_mirror row_mask:0xf bank_mask:0xf
	ds_bpermute_b32 v2, v158, v1
	s_waitcnt lgkmcnt(0)
	v_add_f32_e32 v1, v1, v2
	v_fmamk_f32 v1, v1, 0x3c000000, v160
	v_mul_f32_e32 v2, 0x4f800000, v1
	v_cmp_gt_f32_e32 vcc, s74, v1
	s_nop 1
	v_cndmask_b32_e32 v1, v1, v2, vcc
	v_sqrt_f32_e32 v17, v1
	v_add_co_u32_e64 v2, s[4:5], s54, v64
	v_add_u32_e32 v18, -1, v17
	s_nop 0
	v_addc_co_u32_e64 v3, s[4:5], 0, v65, s[4:5]
	v_add_u32_e32 v19, 1, v17
	v_fma_f32 v33, -v18, v17, v1
	v_fma_f32 v34, -v19, v17, v1
	v_cmp_ge_f32_e64 s[4:5], 0, v33
	s_nop 1
	v_cndmask_b32_e64 v17, v17, v18, s[4:5]
	v_cmp_lt_f32_e64 s[4:5], 0, v34
	s_nop 1
	v_cndmask_b32_e64 v17, v17, v19, s[4:5]
	v_mul_f32_e32 v18, 0x37800000, v17
	v_cndmask_b32_e32 v17, v17, v18, vcc
	v_cmp_class_f32_e32 vcc, v1, v161
	s_nop 1
	v_cndmask_b32_e32 v1, v17, v1, vcc
	v_div_scale_f32 v17, s[4:5], v1, v1, 1.0
	v_rcp_f32_e32 v33, v17
	v_add_co_u32_e32 v18, vcc, s78, v64
	v_fma_f32 v35, -v17, v33, 1.0
	s_nop 0
	v_addc_co_u32_e32 v19, vcc, 0, v65, vcc
	v_div_scale_f32 v34, vcc, 1.0, v1, 1.0
	v_fmac_f32_e32 v33, v35, v33
	v_mul_f32_e32 v35, v34, v33
	v_fma_f32 v49, -v17, v35, v34
	v_fmac_f32_e32 v35, v49, v33
	v_fma_f32 v17, -v17, v35, v34
	v_div_fmas_f32 v17, v17, v33, v35
	v_div_fixup_f32 v1, v17, v1, 1.0
	v_mul_f32_e32 v4, v4, v1
	v_mul_f32_e32 v17, v20, v1
	v_mul_f32_e32 v20, v36, v1
	v_mul_f32_e32 v4, v0, v4
	v_mul_f32_e32 v17, v16, v17
	v_mul_f32_e32 v20, v32, v20
	v_bfe_u32 v33, v4, 16, 1
	v_bfe_u32 v34, v17, 16, 1
	v_bfe_u32 v35, v20, 16, 1
	v_add3_u32 v4, v4, v33, s75
	v_mul_f32_e32 v1, v52, v1
	v_add3_u32 v17, v17, v34, s75
	global_store_short_d16_hi v[18:19], v4, off offset:-4096
	global_store_short_d16_hi v[2:3], v17, off offset:64
	v_add3_u32 v4, v20, v35, s75
	v_mul_f32_e32 v1, v48, v1
	global_store_short_d16_hi v[2:3], v4, off offset:128
	v_bfe_u32 v4, v1, 16, 1
	v_add3_u32 v1, v1, v4, s75
	global_store_short_d16_hi v[2:3], v1, off offset:192
	v_mul_f32_e32 v1, v21, v21
	v_fmac_f32_e32 v1, v5, v5
	v_fmac_f32_e32 v1, v37, v37
	v_fmac_f32_e32 v1, v53, v53

; template <bool DIFF> ...
;     ...
;       ss += __shfl_xor(ss, 1); ss += __shfl_xor(ss, 2); ss += __shfl_xor(ss, 4); ss += __shfl_xor(ss, 8); ss += __shfl_xor(ss, 16);
	s_waitcnt lgkmcnt(0)
	s_nop 1
	v_add_f32_dpp v1, v1, v1 quad_perm:[1,0,3,2] row_mask:0xf bank_mask:0xf

; template <bool DIFF> ...
;     ...
;       ss += __shfl_xor(ss, 1); ss += __shfl_xor(ss, 2); ss += __shfl_xor(ss, 4); ss += __shfl_xor(ss, 8); ss += __shfl_xor(ss, 16);
	s_waitcnt lgkmcnt(0)
	s_nop 1
	v_add_f32_dpp v1, v1, v1 quad_perm:[2,3,0,1] row_mask:0xf bank_mask:0xf

; template <bool DIFF> ...
;     ...
;       ss += __shfl_xor(ss, 1); ss += __shfl_xor(ss, 2); ss += __shfl_xor(ss, 4); ss += __shfl_xor(ss, 8); ss += __shfl_xor(ss, 16);
	s_waitcnt lgkmcnt(0)
	s_nop 1
	v_add_f32_dpp v1, v1, v1 row_half_mirror row_mask:0xf bank_mask:0xf

; __device__ __forceinline__ int crow(int r, int hi) { return (r & 3) + 8 * (r >> 2) + 4 * hi; }
; __device__ __forceinline__ unsigned short f2bf(float f) { unsigned u = __float_as_uint(f); return (unsigned short)((u + 0x7fffu + ((u >> 16) & 1u)) >> 16); }
; __device__ __forceinline__ unsigned f2bf(float f) { unsigned u = __float_as_uint(f); return (u + 0x7fffu + ((u >> 16) & 1u)) >> 16; }
; template <bool DIFF> ...
;     ...
;       float ss = o[0][r] * o[0][r] + o[1][r] * o[1][r] + o[2][r] * o[2][r] + o[3][r] * o[3][r];
;       ss += __shfl_xor(ss, 1); ss += __shfl_xor(ss, 2); ss += __shfl_xor(ss, 4); ss += __shfl_xor(ss, 8); ss += __shfl_xor(ss, 16);
;       const float rs = 1.0f / sqrtf(ss * (1.0f / 128.0f) + 1e-6f);
;       bf16* orow = Ow + (size_t)crow(r, hi) * 2048 + r32;
; #pragma unroll
;       for (int d = 0; d < 4; ++d) orow[32 * d] = f2bf(o[d][r] * rs * gsub[d]);
	s_waitcnt lgkmcnt(0)
	s_nop 1
	v_add_f32_dpp v1, v1, v1 row_mirror row_mask:0xf bank_mask:0xf
	ds_bpermute_b32 v2, v158, v1
	s_waitcnt lgkmcnt(0)
	v_add_f32_e32 v1, v1, v2
	v_fmamk_f32 v1, v1, 0x3c000000, v160
	v_mul_f32_e32 v2, 0x4f800000, v1
	v_cmp_gt_f32_e32 vcc, s74, v1
	s_nop 1
	v_cndmask_b32_e32 v1, v1, v2, vcc
	v_sqrt_f32_e32 v2, v1
	s_nop 0
	v_add_u32_e32 v3, -1, v2
	v_add_u32_e32 v4, 1, v2
	v_fma_f32 v17, -v3, v2, v1
	v_fma_f32 v20, -v4, v2, v1
	v_cmp_ge_f32_e64 s[4:5], 0, v17
	s_nop 1
	v_cndmask_b32_e64 v2, v2, v3, s[4:5]
	v_cmp_lt_f32_e64 s[4:5], 0, v20
	s_nop 1
	v_cndmask_b32_e64 v2, v2, v4, s[4:5]
	v_mul_f32_e32 v3, 0x37800000, v2
	v_cndmask_b32_e32 v2, v2, v3, vcc
	v_cmp_class_f32_e32 vcc, v1, v161
	s_nop 1
	v_cndmask_b32_e32 v1, v2, v1, vcc
	v_div_scale_f32 v2, s[4:5], v1, v1, 1.0
	v_rcp_f32_e32 v3, v2
	v_div_scale_f32 v4, vcc, 1.0, v1, 1.0
	v_fma_f32 v17, -v2, v3, 1.0
	v_fmac_f32_e32 v3, v17, v3
	v_mul_f32_e32 v17, v4, v3
	v_fma_f32 v20, -v2, v17, v4
	v_fmac_f32_e32 v17, v20, v3
	v_fma_f32 v2, -v2, v17, v4
	v_div_fmas_f32 v2, v2, v3, v17
	v_div_fixup_f32 v1, v2, v1, 1.0
	v_mul_f32_e32 v2, v5, v1
	v_mul_f32_e32 v3, v21, v1
	v_mul_f32_e32 v4, v37, v1
	v_mul_f32_e32 v1, v53, v1
	v_mul_f32_e32 v2, v0, v2
	v_mul_f32_e32 v3, v16, v3
	v_mul_f32_e32 v4, v32, v4
	v_mul_f32_e32 v1, v48, v1
	v_bfe_u32 v5, v2, 16, 1
	v_bfe_u32 v17, v3, 16, 1
	v_bfe_u32 v20, v4, 16, 1
	v_bfe_u32 v21, v1, 16, 1
	v_add3_u32 v2, v2, v5, s75
	v_add3_u32 v3, v3, v17, s75
	v_add3_u32 v4, v4, v20, s75
	v_add3_u32 v1, v1, v21, s75
	global_store_short_d16_hi v[18:19], v2, off
	global_store_short_d16_hi v[18:19], v3, off offset:64
	global_store_short_d16_hi v[18:19], v4, off offset:128
	global_store_short_d16_hi v[18:19], v1, off offset:192
	v_mul_f32_e32 v1, v22, v22
	v_fmac_f32_e32 v1, v6, v6
	v_fmac_f32_e32 v1, v38, v38
	v_fmac_f32_e32 v1, v54, v54

; template <bool DIFF> ...
;     ...
;       ss += __shfl_xor(ss, 1); ss += __shfl_xor(ss, 2); ss += __shfl_xor(ss, 4); ss += __shfl_xor(ss, 8); ss += __shfl_xor(ss, 16);
	s_waitcnt lgkmcnt(0)
	s_nop 1
	v_add_f32_dpp v1, v1, v1 quad_perm:[1,0,3,2] row_mask:0xf bank_mask:0xf

; template <bool DIFF> ...
;     ...
;       ss += __shfl_xor(ss, 1); ss += __shfl_xor(ss, 2); ss += __shfl_xor(ss, 4); ss += __shfl_xor(ss, 8); ss += __shfl_xor(ss, 16);
	s_waitcnt lgkmcnt(0)
	s_nop 1
	v_add_f32_dpp v1, v1, v1 quad_perm:[2,3,0,1] row_mask:0xf bank_mask:0xf

; template <bool DIFF> ...
;     ...
;       ss += __shfl_xor(ss, 1); ss += __shfl_xor(ss, 2); ss += __shfl_xor(ss, 4); ss += __shfl_xor(ss, 8); ss += __shfl_xor(ss, 16);
	s_waitcnt lgkmcnt(0)
	s_nop 1
	v_add_f32_dpp v1, v1, v1 row_half_mirror row_mask:0xf bank_mask:0xf

; __device__ __forceinline__ int crow(int r, int hi) { return (r & 3) + 8 * (r >> 2) + 4 * hi; }
; __device__ __forceinline__ unsigned short f2bf(float f) { unsigned u = __float_as_uint(f); return (unsigned short)((u + 0x7fffu + ((u >> 16) & 1u)) >> 16); }
; __device__ __forceinline__ unsigned f2bf(float f) { unsigned u = __float_as_uint(f); return (u + 0x7fffu + ((u >> 16) & 1u)) >> 16; }
; template <bool DIFF> ...
;     ...
;       float ss = o[0][r] * o[0][r] + o[1][r] * o[1][r] + o[2][r] * o[2][r] + o[3][r] * o[3][r];
;       ss += __shfl_xor(ss, 1); ss += __shfl_xor(ss, 2); ss += __shfl_xor(ss, 4); ss += __shfl_xor(ss, 8); ss += __shfl_xor(ss, 16);
;       const float rs = 1.0f / sqrtf(ss * (1.0f / 128.0f) + 1e-6f);
;       bf16* orow = Ow + (size_t)crow(r, hi) * 2048 + r32;
; #pragma unroll
;       for (int d = 0; d < 4; ++d) orow[32 * d] = f2bf(o[d][r] * rs * gsub[d]);
	s_waitcnt lgkmcnt(0)
	s_nop 1
	v_add_f32_dpp v1, v1, v1 row_mirror row_mask:0xf bank_mask:0xf
	ds_bpermute_b32 v2, v158, v1
	s_waitcnt lgkmcnt(0)
	v_add_f32_e32 v1, v1, v2
	v_fmamk_f32 v1, v1, 0x3c000000, v160
	v_mul_f32_e32 v2, 0x4f800000, v1
	v_cmp_gt_f32_e32 vcc, s74, v1
	s_nop 1
	v_cndmask_b32_e32 v1, v1, v2, vcc
	v_sqrt_f32_e32 v4, v1
	v_add_co_u32_e64 v2, s[4:5], s79, v64
	v_add_u32_e32 v5, -1, v4
	s_nop 0
	v_addc_co_u32_e64 v3, s[4:5], 0, v65, s[4:5]
	v_add_u32_e32 v17, 1, v4
	v_fma_f32 v18, -v5, v4, v1
	v_fma_f32 v19, -v17, v4, v1
	v_cmp_ge_f32_e64 s[4:5], 0, v18
	s_nop 1
	v_cndmask_b32_e64 v4, v4, v5, s[4:5]
	v_cmp_lt_f32_e64 s[4:5], 0, v19
	s_nop 1
	v_cndmask_b32_e64 v4, v4, v17, s[4:5]
	v_mul_f32_e32 v5, 0x37800000, v4
	v_cndmask_b32_e32 v4, v4, v5, vcc
	v_cmp_class_f32_e32 vcc, v1, v161
	s_nop 1
	v_cndmask_b32_e32 v1, v4, v1, vcc
	v_div_scale_f32 v17, s[4:5], v1, v1, 1.0
	v_rcp_f32_e32 v18, v17
	v_add_co_u32_e32 v4, vcc, s80, v64
	v_fma_f32 v20, -v17, v18, 1.0
	s_nop 0
	v_addc_co_u32_e32 v5, vcc, 0, v65, vcc
	v_div_scale_f32 v19, vcc, 1.0, v1, 1.0
	v_fmac_f32_e32 v18, v20, v18
	v_mul_f32_e32 v20, v19, v18
	v_fma_f32 v21, -v17, v20, v19
	v_fmac_f32_e32 v20, v21, v18
	v_fma_f32 v17, -v17, v20, v19
	v_div_fmas_f32 v17, v17, v18, v20
	v_div_fixup_f32 v1, v17, v1, 1.0
	v_mul_f32_e32 v6, v6, v1
	v_mul_f32_e32 v17, v22, v1
	v_mul_f32_e32 v18, v38, v1
	v_mul_f32_e32 v6, v0, v6
	v_mul_f32_e32 v17, v16, v17
	v_mul_f32_e32 v18, v32, v18
	v_bfe_u32 v19, v6, 16, 1
	v_bfe_u32 v20, v17, 16, 1
	v_bfe_u32 v21, v18, 16, 1
	v_add3_u32 v6, v6, v19, s75
	v_mul_f32_e32 v1, v54, v1
	v_add3_u32 v17, v17, v20, s75
	global_store_short_d16_hi v[4:5], v6, off offset:-4096
	global_store_short_d16_hi v[2:3], v17, off offset:64
	v_add3_u32 v6, v18, v21, s75
	v_mul_f32_e32 v1, v48, v1
	global_store_short_d16_hi v[2:3], v6, off offset:128
	v_bfe_u32 v6, v1, 16, 1
	v_add3_u32 v1, v1, v6, s75
	global_store_short_d16_hi v[2:3], v1, off offset:192
	v_mul_f32_e32 v1, v23, v23
	v_fmac_f32_e32 v1, v7, v7
	v_fmac_f32_e32 v1, v39, v39
	v_fmac_f32_e32 v1, v55, v55

; template <bool DIFF> ...
;     ...
;       ss += __shfl_xor(ss, 1); ss += __shfl_xor(ss, 2); ss += __shfl_xor(ss, 4); ss += __shfl_xor(ss, 8); ss += __shfl_xor(ss, 16);
	s_waitcnt lgkmcnt(0)
	s_nop 1
	v_add_f32_dpp v1, v1, v1 quad_perm:[1,0,3,2] row_mask:0xf bank_mask:0xf

; template <bool DIFF> ...
;     ...
;       ss += __shfl_xor(ss, 1); ss += __shfl_xor(ss, 2); ss += __shfl_xor(ss, 4); ss += __shfl_xor(ss, 8); ss += __shfl_xor(ss, 16);
	s_waitcnt lgkmcnt(0)
	s_nop 1
	v_add_f32_dpp v1, v1, v1 quad_perm:[2,3,0,1] row_mask:0xf bank_mask:0xf

; template <bool DIFF> ...
;     ...
;       ss += __shfl_xor(ss, 1); ss += __shfl_xor(ss, 2); ss += __shfl_xor(ss, 4); ss += __shfl_xor(ss, 8); ss += __shfl_xor(ss, 16);
	s_waitcnt lgkmcnt(0)
	s_nop 1
	v_add_f32_dpp v1, v1, v1 row_half_mirror row_mask:0xf bank_mask:0xf

; __device__ __forceinline__ int crow(int r, int hi) { return (r & 3) + 8 * (r >> 2) + 4 * hi; }
; __device__ __forceinline__ unsigned short f2bf(float f) { unsigned u = __float_as_uint(f); return (unsigned short)((u + 0x7fffu + ((u >> 16) & 1u)) >> 16); }
; __device__ __forceinline__ unsigned f2bf(float f) { unsigned u = __float_as_uint(f); return (u + 0x7fffu + ((u >> 16) & 1u)) >> 16; }
; template <bool DIFF> ...
;     ...
;       float ss = o[0][r] * o[0][r] + o[1][r] * o[1][r] + o[2][r] * o[2][r] + o[3][r] * o[3][r];
;       ss += __shfl_xor(ss, 1); ss += __shfl_xor(ss, 2); ss += __shfl_xor(ss, 4); ss += __shfl_xor(ss, 8); ss += __shfl_xor(ss, 16);
;       const float rs = 1.0f / sqrtf(ss * (1.0f / 128.0f) + 1e-6f);
;       bf16* orow = Ow + (size_t)crow(r, hi) * 2048 + r32;
; #pragma unroll
;       for (int d = 0; d < 4; ++d) orow[32 * d] = f2bf(o[d][r] * rs * gsub[d]);
	s_waitcnt lgkmcnt(0)
	s_nop 1
	v_add_f32_dpp v1, v1, v1 row_mirror row_mask:0xf bank_mask:0xf
	ds_bpermute_b32 v2, v158, v1
	s_waitcnt lgkmcnt(0)
	v_add_f32_e32 v1, v1, v2
	v_fmamk_f32 v1, v1, 0x3c000000, v160
	v_mul_f32_e32 v2, 0x4f800000, v1
	v_cmp_gt_f32_e32 vcc, s74, v1
	s_nop 1
	v_cndmask_b32_e32 v1, v1, v2, vcc
	v_sqrt_f32_e32 v2, v1
	s_nop 0
	v_add_u32_e32 v3, -1, v2
	v_add_u32_e32 v6, 1, v2
	v_fma_f32 v17, -v3, v2, v1
	v_fma_f32 v18, -v6, v2, v1
	v_cmp_ge_f32_e64 s[4:5], 0, v17
	s_nop 1
	v_cndmask_b32_e64 v2, v2, v3, s[4:5]
	v_cmp_lt_f32_e64 s[4:5], 0, v18
	s_nop 1
	v_cndmask_b32_e64 v2, v2, v6, s[4:5]
	v_mul_f32_e32 v3, 0x37800000, v2
	v_cndmask_b32_e32 v2, v2, v3, vcc
	v_cmp_class_f32_e32 vcc, v1, v161
	s_nop 1
	v_cndmask_b32_e32 v1, v2, v1, vcc
	v_div_scale_f32 v2, s[4:5], v1, v1, 1.0
	v_rcp_f32_e32 v3, v2
	v_div_scale_f32 v6, vcc, 1.0, v1, 1.0
	v_fma_f32 v17, -v2, v3, 1.0
	v_fmac_f32_e32 v3, v17, v3
	v_mul_f32_e32 v17, v6, v3
	v_fma_f32 v18, -v2, v17, v6
	v_fmac_f32_e32 v17, v18, v3
	v_fma_f32 v2, -v2, v17, v6
	v_div_fmas_f32 v2, v2, v3, v17
	v_div_fixup_f32 v1, v2, v1, 1.0
	v_mul_f32_e32 v2, v7, v1
	v_mul_f32_e32 v3, v23, v1
	v_mul_f32_e32 v6, v39, v1
	v_mul_f32_e32 v1, v55, v1
	v_mul_f32_e32 v2, v0, v2
	v_mul_f32_e32 v3, v16, v3
	v_mul_f32_e32 v6, v32, v6
	v_mul_f32_e32 v1, v48, v1
	v_bfe_u32 v7, v2, 16, 1
	v_bfe_u32 v17, v3, 16, 1
	v_bfe_u32 v18, v6, 16, 1
	v_bfe_u32 v19, v1, 16, 1
	v_add3_u32 v2, v2, v7, s75
	v_add3_u32 v3, v3, v17, s75
	v_add3_u32 v6, v6, v18, s75
	v_add3_u32 v1, v1, v19, s75
	global_store_short_d16_hi v[4:5], v2, off
	global_store_short_d16_hi v[4:5], v3, off offset:64
	global_store_short_d16_hi v[4:5], v6, off offset:128
	global_store_short_d16_hi v[4:5], v1, off offset:192
	v_mul_f32_e32 v1, v24, v24
	v_fmac_f32_e32 v1, v8, v8
	v_fmac_f32_e32 v1, v40, v40
	v_fmac_f32_e32 v1, v56, v56

; template <bool DIFF> ...
;     ...
;       ss += __shfl_xor(ss, 1); ss += __shfl_xor(ss, 2); ss += __shfl_xor(ss, 4); ss += __shfl_xor(ss, 8); ss += __shfl_xor(ss, 16);
	s_waitcnt lgkmcnt(0)
	s_nop 1
	v_add_f32_dpp v1, v1, v1 quad_perm:[1,0,3,2] row_mask:0xf bank_mask:0xf

; template <bool DIFF> ...
;     ...
;       ss += __shfl_xor(ss, 1); ss += __shfl_xor(ss, 2); ss += __shfl_xor(ss, 4); ss += __shfl_xor(ss, 8); ss += __shfl_xor(ss, 16);
	s_waitcnt lgkmcnt(0)
	s_nop 1
	v_add_f32_dpp v1, v1, v1 quad_perm:[2,3,0,1] row_mask:0xf bank_mask:0xf

; template <bool DIFF> ...
;     ...
;       ss += __shfl_xor(ss, 1); ss += __shfl_xor(ss, 2); ss += __shfl_xor(ss, 4); ss += __shfl_xor(ss, 8); ss += __shfl_xor(ss, 16);
	s_waitcnt lgkmcnt(0)
	s_nop 1
	v_add_f32_dpp v1, v1, v1 row_half_mirror row_mask:0xf bank_mask:0xf

; __device__ __forceinline__ int crow(int r, int hi) { return (r & 3) + 8 * (r >> 2) + 4 * hi; }
; __device__ __forceinline__ unsigned short f2bf(float f) { unsigned u = __float_as_uint(f); return (unsigned short)((u + 0x7fffu + ((u >> 16) & 1u)) >> 16); }
; __device__ __forceinline__ unsigned f2bf(float f) { unsigned u = __float_as_uint(f); return (u + 0x7fffu + ((u >> 16) & 1u)) >> 16; }
; template <bool DIFF> ...
;     ...
;       float ss = o[0][r] * o[0][r] + o[1][r] * o[1][r] + o[2][r] * o[2][r] + o[3][r] * o[3][r];
;       ss += __shfl_xor(ss, 1); ss += __shfl_xor(ss, 2); ss += __shfl_xor(ss, 4); ss += __shfl_xor(ss, 8); ss += __shfl_xor(ss, 16);
;       const float rs = 1.0f / sqrtf(ss * (1.0f / 128.0f) + 1e-6f);
;       bf16* orow = Ow + (size_t)crow(r, hi) * 2048 + r32;
; #pragma unroll
;       for (int d = 0; d < 4; ++d) orow[32 * d] = f2bf(o[d][r] * rs * gsub[d]);
	s_waitcnt lgkmcnt(0)
	s_nop 1
	v_add_f32_dpp v1, v1, v1 row_mirror row_mask:0xf bank_mask:0xf
	ds_bpermute_b32 v2, v158, v1
	s_waitcnt lgkmcnt(0)
	v_add_f32_e32 v1, v1, v2
	v_fmamk_f32 v1, v1, 0x3c000000, v160
	v_mul_f32_e32 v2, 0x4f800000, v1
	v_cmp_gt_f32_e32 vcc, s74, v1
	s_nop 1
	v_cndmask_b32_e32 v1, v1, v2, vcc
	v_sqrt_f32_e32 v4, v1
	v_add_co_u32_e64 v2, s[4:5], s66, v64
	v_add_u32_e32 v5, -1, v4
	s_nop 0
	v_addc_co_u32_e64 v3, s[4:5], 0, v65, s[4:5]
	v_add_u32_e32 v6, 1, v4
	v_fma_f32 v7, -v5, v4, v1
	v_fma_f32 v17, -v6, v4, v1
	v_cmp_ge_f32_e64 s[4:5], 0, v7
	s_nop 1
	v_cndmask_b32_e64 v4, v4, v5, s[4:5]
	v_cmp_lt_f32_e64 s[4:5], 0, v17
	s_nop 1
	v_cndmask_b32_e64 v4, v4, v6, s[4:5]
	v_mul_f32_e32 v5, 0x37800000, v4
	v_cndmask_b32_e32 v4, v4, v5, vcc
	v_cmp_class_f32_e32 vcc, v1, v161
	s_nop 1
	v_cndmask_b32_e32 v1, v4, v1, vcc
	v_div_scale_f32 v6, s[4:5], v1, v1, 1.0
	v_rcp_f32_e32 v7, v6
	v_add_co_u32_e32 v4, vcc, s81, v64
	v_fma_f32 v18, -v6, v7, 1.0
	s_nop 0
	v_addc_co_u32_e32 v5, vcc, 0, v65, vcc
	v_div_scale_f32 v17, vcc, 1.0, v1, 1.0
	v_fmac_f32_e32 v7, v18, v7
	v_mul_f32_e32 v18, v17, v7
	v_fma_f32 v19, -v6, v18, v17
	v_fmac_f32_e32 v18, v19, v7
	v_fma_f32 v6, -v6, v18, v17
	v_div_fmas_f32 v6, v6, v7, v18
	v_div_fixup_f32 v1, v6, v1, 1.0
	v_mul_f32_e32 v6, v8, v1
	v_mul_f32_e32 v7, v24, v1
	v_mul_f32_e32 v8, v40, v1
	v_mul_f32_e32 v6, v0, v6
	v_mul_f32_e32 v7, v16, v7
	v_mul_f32_e32 v8, v32, v8
	v_bfe_u32 v17, v6, 16, 1
	v_bfe_u32 v18, v7, 16, 1
	v_bfe_u32 v19, v8, 16, 1
	v_add3_u32 v6, v6, v17, s75
	v_mul_f32_e32 v1, v56, v1
	v_add3_u32 v7, v7, v18, s75
	global_store_short_d16_hi v[4:5], v6, off offset:-4096
	global_store_short_d16_hi v[2:3], v7, off offset:64
	v_add3_u32 v6, v8, v19, s75
	v_mul_f32_e32 v1, v48, v1
	global_store_short_d16_hi v[2:3], v6, off offset:128
	v_bfe_u32 v6, v1, 16, 1
	v_add3_u32 v1, v1, v6, s75
	global_store_short_d16_hi v[2:3], v1, off offset:192
	v_mul_f32_e32 v1, v25, v25
	v_fmac_f32_e32 v1, v9, v9
	v_fmac_f32_e32 v1, v41, v41
	v_fmac_f32_e32 v1, v57, v57

; template <bool DIFF> ...
;     ...
;       ss += __shfl_xor(ss, 1); ss += __shfl_xor(ss, 2); ss += __shfl_xor(ss, 4); ss += __shfl_xor(ss, 8); ss += __shfl_xor(ss, 16);
	s_waitcnt lgkmcnt(0)
	s_nop 1
	v_add_f32_dpp v1, v1, v1 quad_perm:[1,0,3,2] row_mask:0xf bank_mask:0xf

; template <bool DIFF> ...
;     ...
;       ss += __shfl_xor(ss, 1); ss += __shfl_xor(ss, 2); ss += __shfl_xor(ss, 4); ss += __shfl_xor(ss, 8); ss += __shfl_xor(ss, 16);
	s_waitcnt lgkmcnt(0)
	s_nop 1
	v_add_f32_dpp v1, v1, v1 quad_perm:[2,3,0,1] row_mask:0xf bank_mask:0xf

; template <bool DIFF> ...
;     ...
;       ss += __shfl_xor(ss, 1); ss += __shfl_xor(ss, 2); ss += __shfl_xor(ss, 4); ss += __shfl_xor(ss, 8); ss += __shfl_xor(ss, 16);
	s_waitcnt lgkmcnt(0)
	s_nop 1
	v_add_f32_dpp v1, v1, v1 row_half_mirror row_mask:0xf bank_mask:0xf

; __device__ __forceinline__ int crow(int r, int hi) { return (r & 3) + 8 * (r >> 2) + 4 * hi; }
; __device__ __forceinline__ unsigned short f2bf(float f) { unsigned u = __float_as_uint(f); return (unsigned short)((u + 0x7fffu + ((u >> 16) & 1u)) >> 16); }
; __device__ __forceinline__ unsigned f2bf(float f) { unsigned u = __float_as_uint(f); return (u + 0x7fffu + ((u >> 16) & 1u)) >> 16; }
; template <bool DIFF> ...
;     ...
;       float ss = o[0][r] * o[0][r] + o[1][r] * o[1][r] + o[2][r] * o[2][r] + o[3][r] * o[3][r];
;       ss += __shfl_xor(ss, 1); ss += __shfl_xor(ss, 2); ss += __shfl_xor(ss, 4); ss += __shfl_xor(ss, 8); ss += __shfl_xor(ss, 16);
;       const float rs = 1.0f / sqrtf(ss * (1.0f / 128.0f) + 1e-6f);
;       bf16* orow = Ow + (size_t)crow(r, hi) * 2048 + r32;
; #pragma unroll
;       for (int d = 0; d < 4; ++d) orow[32 * d] = f2bf(o[d][r] * rs * gsub[d]);
	s_waitcnt lgkmcnt(0)
	s_nop 1
	v_add_f32_dpp v1, v1, v1 row_mirror row_mask:0xf bank_mask:0xf
	ds_bpermute_b32 v2, v158, v1
	s_waitcnt lgkmcnt(0)
	v_add_f32_e32 v1, v1, v2
	v_fmamk_f32 v1, v1, 0x3c000000, v160
	v_mul_f32_e32 v2, 0x4f800000, v1
	v_cmp_gt_f32_e32 vcc, s74, v1
	s_nop 1
	v_cndmask_b32_e32 v1, v1, v2, vcc
	v_sqrt_f32_e32 v2, v1
	s_nop 0
	v_add_u32_e32 v3, -1, v2
	v_add_u32_e32 v6, 1, v2
	v_fma_f32 v7, -v3, v2, v1
	v_fma_f32 v8, -v6, v2, v1
	v_cmp_ge_f32_e64 s[4:5], 0, v7
	s_nop 1
	v_cndmask_b32_e64 v2, v2, v3, s[4:5]
	v_cmp_lt_f32_e64 s[4:5], 0, v8
	s_nop 1
	v_cndmask_b32_e64 v2, v2, v6, s[4:5]
	v_mul_f32_e32 v3, 0x37800000, v2
	v_cndmask_b32_e32 v2, v2, v3, vcc
	v_cmp_class_f32_e32 vcc, v1, v161
	s_nop 1
	v_cndmask_b32_e32 v1, v2, v1, vcc
	v_div_scale_f32 v2, s[4:5], v1, v1, 1.0
	v_rcp_f32_e32 v3, v2
	v_div_scale_f32 v6, vcc, 1.0, v1, 1.0
	v_fma_f32 v7, -v2, v3, 1.0
	v_fmac_f32_e32 v3, v7, v3
	v_mul_f32_e32 v7, v6, v3
	v_fma_f32 v8, -v2, v7, v6
	v_fmac_f32_e32 v7, v8, v3
	v_fma_f32 v2, -v2, v7, v6
	v_div_fmas_f32 v2, v2, v3, v7
	v_div_fixup_f32 v1, v2, v1, 1.0
	v_mul_f32_e32 v2, v9, v1
	v_mul_f32_e32 v3, v25, v1
	v_mul_f32_e32 v6, v41, v1
	v_mul_f32_e32 v1, v57, v1
	v_mul_f32_e32 v2, v0, v2
	v_mul_f32_e32 v3, v16, v3
	v_mul_f32_e32 v6, v32, v6
	v_mul_f32_e32 v1, v48, v1
	v_bfe_u32 v7, v2, 16, 1
	v_bfe_u32 v8, v3, 16, 1
	v_bfe_u32 v9, v6, 16, 1
	v_bfe_u32 v17, v1, 16, 1
	v_add3_u32 v2, v2, v7, s75
	v_add3_u32 v3, v3, v8, s75
	v_add3_u32 v6, v6, v9, s75
	v_add3_u32 v1, v1, v17, s75
	global_store_short_d16_hi v[4:5], v2, off
	global_store_short_d16_hi v[4:5], v3, off offset:64
	global_store_short_d16_hi v[4:5], v6, off offset:128
	global_store_short_d16_hi v[4:5], v1, off offset:192
	v_mul_f32_e32 v1, v26, v26
	v_fmac_f32_e32 v1, v10, v10
	v_fmac_f32_e32 v1, v42, v42
	v_fmac_f32_e32 v1, v58, v58

; template <bool DIFF> ...
;     ...
;       ss += __shfl_xor(ss, 1); ss += __shfl_xor(ss, 2); ss += __shfl_xor(ss, 4); ss += __shfl_xor(ss, 8); ss += __shfl_xor(ss, 16);
	s_waitcnt lgkmcnt(0)
	s_nop 1
	v_add_f32_dpp v1, v1, v1 quad_perm:[1,0,3,2] row_mask:0xf bank_mask:0xf

; template <bool DIFF> ...
;     ...
;       ss += __shfl_xor(ss, 1); ss += __shfl_xor(ss, 2); ss += __shfl_xor(ss, 4); ss += __shfl_xor(ss, 8); ss += __shfl_xor(ss, 16);
	s_waitcnt lgkmcnt(0)
	s_nop 1
	v_add_f32_dpp v1, v1, v1 quad_perm:[2,3,0,1] row_mask:0xf bank_mask:0xf

; template <bool DIFF> ...
;     ...
;       ss += __shfl_xor(ss, 1); ss += __shfl_xor(ss, 2); ss += __shfl_xor(ss, 4); ss += __shfl_xor(ss, 8); ss += __shfl_xor(ss, 16);
	s_waitcnt lgkmcnt(0)
	s_nop 1
	v_add_f32_dpp v1, v1, v1 row_half_mirror row_mask:0xf bank_mask:0xf

; __device__ __forceinline__ int crow(int r, int hi) { return (r & 3) + 8 * (r >> 2) + 4 * hi; }
; __device__ __forceinline__ unsigned short f2bf(float f) { unsigned u = __float_as_uint(f); return (unsigned short)((u + 0x7fffu + ((u >> 16) & 1u)) >> 16); }
; __device__ __forceinline__ unsigned f2bf(float f) { unsigned u = __float_as_uint(f); return (u + 0x7fffu + ((u >> 16) & 1u)) >> 16; }
; template <bool DIFF> ...
;     ...
;       float ss = o[0][r] * o[0][r] + o[1][r] * o[1][r] + o[2][r] * o[2][r] + o[3][r] * o[3][r];
;       ss += __shfl_xor(ss, 1); ss += __shfl_xor(ss, 2); ss += __shfl_xor(ss, 4); ss += __shfl_xor(ss, 8); ss += __shfl_xor(ss, 16);
;       const float rs = 1.0f / sqrtf(ss * (1.0f / 128.0f) + 1e-6f);
;       bf16* orow = Ow + (size_t)crow(r, hi) * 2048 + r32;
; #pragma unroll
;       for (int d = 0; d < 4; ++d) orow[32 * d] = f2bf(o[d][r] * rs * gsub[d]);
	s_waitcnt lgkmcnt(0)
	s_nop 1
	v_add_f32_dpp v1, v1, v1 row_mirror row_mask:0xf bank_mask:0xf
	ds_bpermute_b32 v2, v158, v1
	s_waitcnt lgkmcnt(0)
	v_add_f32_e32 v1, v1, v2
	v_fmamk_f32 v1, v1, 0x3c000000, v160
	v_mul_f32_e32 v2, 0x4f800000, v1
	v_cmp_gt_f32_e32 vcc, s74, v1
	s_nop 1
	v_cndmask_b32_e32 v1, v1, v2, vcc
	v_sqrt_f32_e32 v4, v1
	v_add_co_u32_e64 v2, s[4:5], s82, v64
	v_add_u32_e32 v5, -1, v4
	s_nop 0
	v_addc_co_u32_e64 v3, s[4:5], 0, v65, s[4:5]
	v_add_u32_e32 v6, 1, v4
	v_fma_f32 v7, -v5, v4, v1
	v_fma_f32 v8, -v6, v4, v1
	v_cmp_ge_f32_e64 s[4:5], 0, v7
	s_nop 1
	v_cndmask_b32_e64 v4, v4, v5, s[4:5]
	v_cmp_lt_f32_e64 s[4:5], 0, v8
	s_nop 1
	v_cndmask_b32_e64 v4, v4, v6, s[4:5]
	v_mul_f32_e32 v5, 0x37800000, v4
	v_cndmask_b32_e32 v4, v4, v5, vcc
	v_cmp_class_f32_e32 vcc, v1, v161
	s_nop 1
	v_cndmask_b32_e32 v1, v4, v1, vcc
	v_div_scale_f32 v6, s[4:5], v1, v1, 1.0
	v_rcp_f32_e32 v7, v6
	v_add_co_u32_e32 v4, vcc, s83, v64
	v_fma_f32 v9, -v6, v7, 1.0
	s_nop 0
	v_addc_co_u32_e32 v5, vcc, 0, v65, vcc
	v_div_scale_f32 v8, vcc, 1.0, v1, 1.0
	v_fmac_f32_e32 v7, v9, v7
	v_mul_f32_e32 v9, v8, v7
	v_fma_f32 v17, -v6, v9, v8
	v_fmac_f32_e32 v9, v17, v7
	v_fma_f32 v6, -v6, v9, v8
	v_div_fmas_f32 v6, v6, v7, v9
	v_div_fixup_f32 v1, v6, v1, 1.0
	v_mul_f32_e32 v6, v10, v1
	v_mul_f32_e32 v7, v26, v1
	v_mul_f32_e32 v8, v42, v1
	v_mul_f32_e32 v6, v0, v6
	v_mul_f32_e32 v7, v16, v7
	v_mul_f32_e32 v8, v32, v8
	v_bfe_u32 v9, v6, 16, 1
	v_bfe_u32 v10, v7, 16, 1
	v_bfe_u32 v17, v8, 16, 1
	v_add3_u32 v6, v6, v9, s75
	v_mul_f32_e32 v1, v58, v1
	v_add3_u32 v7, v7, v10, s75
	global_store_short_d16_hi v[4:5], v6, off offset:-4096
	global_store_short_d16_hi v[2:3], v7, off offset:64
	v_add3_u32 v6, v8, v17, s75
	v_mul_f32_e32 v1, v48, v1
	global_store_short_d16_hi v[2:3], v6, off offset:128
	v_bfe_u32 v6, v1, 16, 1
	v_add3_u32 v1, v1, v6, s75
	global_store_short_d16_hi v[2:3], v1, off offset:192
	v_mul_f32_e32 v1, v27, v27
	v_fmac_f32_e32 v1, v11, v11
	v_fmac_f32_e32 v1, v43, v43
	v_fmac_f32_e32 v1, v59, v59

; template <bool DIFF> ...
;     ...
;       ss += __shfl_xor(ss, 1); ss += __shfl_xor(ss, 2); ss += __shfl_xor(ss, 4); ss += __shfl_xor(ss, 8); ss += __shfl_xor(ss, 16);
	s_waitcnt lgkmcnt(0)
	s_nop 1
	v_add_f32_dpp v1, v1, v1 quad_perm:[1,0,3,2] row_mask:0xf bank_mask:0xf

; template <bool DIFF> ...
;     ...
;       ss += __shfl_xor(ss, 1); ss += __shfl_xor(ss, 2); ss += __shfl_xor(ss, 4); ss += __shfl_xor(ss, 8); ss += __shfl_xor(ss, 16);
	s_waitcnt lgkmcnt(0)
	s_nop 1
	v_add_f32_dpp v1, v1, v1 quad_perm:[2,3,0,1] row_mask:0xf bank_mask:0xf

; template <bool DIFF> ...
;     ...
;       ss += __shfl_xor(ss, 1); ss += __shfl_xor(ss, 2); ss += __shfl_xor(ss, 4); ss += __shfl_xor(ss, 8); ss += __shfl_xor(ss, 16);
	s_waitcnt lgkmcnt(0)
	s_nop 1
	v_add_f32_dpp v1, v1, v1 row_half_mirror row_mask:0xf bank_mask:0xf

; __device__ __forceinline__ int crow(int r, int hi) { return (r & 3) + 8 * (r >> 2) + 4 * hi; }
; __device__ __forceinline__ unsigned short f2bf(float f) { unsigned u = __float_as_uint(f); return (unsigned short)((u + 0x7fffu + ((u >> 16) & 1u)) >> 16); }
; __device__ __forceinline__ unsigned f2bf(float f) { unsigned u = __float_as_uint(f); return (u + 0x7fffu + ((u >> 16) & 1u)) >> 16; }
; template <bool DIFF> ...
;     ...
;       float ss = o[0][r] * o[0][r] + o[1][r] * o[1][r] + o[2][r] * o[2][r] + o[3][r] * o[3][r];
;       ss += __shfl_xor(ss, 1); ss += __shfl_xor(ss, 2); ss += __shfl_xor(ss, 4); ss += __shfl_xor(ss, 8); ss += __shfl_xor(ss, 16);
;       const float rs = 1.0f / sqrtf(ss * (1.0f / 128.0f) + 1e-6f);
;       bf16* orow = Ow + (size_t)crow(r, hi) * 2048 + r32;
; #pragma unroll
;       for (int d = 0; d < 4; ++d) orow[32 * d] = f2bf(o[d][r] * rs * gsub[d]);
	s_waitcnt lgkmcnt(0)
	s_nop 1
	v_add_f32_dpp v1, v1, v1 row_mirror row_mask:0xf bank_mask:0xf
	ds_bpermute_b32 v2, v158, v1
	s_waitcnt lgkmcnt(0)
	v_add_f32_e32 v1, v1, v2
	v_fmamk_f32 v1, v1, 0x3c000000, v160
	v_mul_f32_e32 v2, 0x4f800000, v1
	v_cmp_gt_f32_e32 vcc, s74, v1
	s_nop 1
	v_cndmask_b32_e32 v1, v1, v2, vcc
	v_sqrt_f32_e32 v2, v1
	s_nop 0
	v_add_u32_e32 v3, -1, v2
	v_add_u32_e32 v6, 1, v2
	v_fma_f32 v7, -v3, v2, v1
	v_fma_f32 v8, -v6, v2, v1
	v_cmp_ge_f32_e64 s[4:5], 0, v7
	s_nop 1
	v_cndmask_b32_e64 v2, v2, v3, s[4:5]
	v_cmp_lt_f32_e64 s[4:5], 0, v8
	s_nop 1
	v_cndmask_b32_e64 v2, v2, v6, s[4:5]
	v_mul_f32_e32 v3, 0x37800000, v2
	v_cndmask_b32_e32 v2, v2, v3, vcc
	v_cmp_class_f32_e32 vcc, v1, v161
	s_nop 1
	v_cndmask_b32_e32 v1, v2, v1, vcc
	v_div_scale_f32 v2, s[4:5], v1, v1, 1.0
	v_rcp_f32_e32 v3, v2
	v_div_scale_f32 v6, vcc, 1.0, v1, 1.0
	v_fma_f32 v7, -v2, v3, 1.0
	v_fmac_f32_e32 v3, v7, v3
	v_mul_f32_e32 v7, v6, v3
	v_fma_f32 v8, -v2, v7, v6
	v_fmac_f32_e32 v7, v8, v3
	v_fma_f32 v2, -v2, v7, v6
	v_div_fmas_f32 v2, v2, v3, v7
	v_div_fixup_f32 v1, v2, v1, 1.0
	v_mul_f32_e32 v2, v11, v1
	v_mul_f32_e32 v3, v27, v1
	v_mul_f32_e32 v6, v43, v1
	v_mul_f32_e32 v1, v59, v1
	v_mul_f32_e32 v2, v0, v2
	v_mul_f32_e32 v3, v16, v3
	v_mul_f32_e32 v6, v32, v6
	v_mul_f32_e32 v1, v48, v1
	v_bfe_u32 v7, v2, 16, 1
	v_bfe_u32 v8, v3, 16, 1
	v_bfe_u32 v9, v6, 16, 1
	v_bfe_u32 v10, v1, 16, 1
	v_add3_u32 v2, v2, v7, s75
	v_add3_u32 v3, v3, v8, s75
	v_add3_u32 v6, v6, v9, s75
	v_add3_u32 v1, v1, v10, s75
	global_store_short_d16_hi v[4:5], v2, off
	global_store_short_d16_hi v[4:5], v3, off offset:64
	global_store_short_d16_hi v[4:5], v6, off offset:128
	global_store_short_d16_hi v[4:5], v1, off offset:192
	v_mul_f32_e32 v1, v28, v28
	v_fmac_f32_e32 v1, v12, v12
	v_fmac_f32_e32 v1, v44, v44
	v_fmac_f32_e32 v1, v60, v60

; template <bool DIFF> ...
;     ...
;       ss += __shfl_xor(ss, 1); ss += __shfl_xor(ss, 2); ss += __shfl_xor(ss, 4); ss += __shfl_xor(ss, 8); ss += __shfl_xor(ss, 16);
	s_waitcnt lgkmcnt(0)
	s_nop 1
	v_add_f32_dpp v1, v1, v1 quad_perm:[1,0,3,2] row_mask:0xf bank_mask:0xf

; template <bool DIFF> ...
;     ...
;       ss += __shfl_xor(ss, 1); ss += __shfl_xor(ss, 2); ss += __shfl_xor(ss, 4); ss += __shfl_xor(ss, 8); ss += __shfl_xor(ss, 16);
	s_waitcnt lgkmcnt(0)
	s_nop 1
	v_add_f32_dpp v1, v1, v1 quad_perm:[2,3,0,1] row_mask:0xf bank_mask:0xf

; template <bool DIFF> ...
;     ...
;       ss += __shfl_xor(ss, 1); ss += __shfl_xor(ss, 2); ss += __shfl_xor(ss, 4); ss += __shfl_xor(ss, 8); ss += __shfl_xor(ss, 16);
	s_waitcnt lgkmcnt(0)
	s_nop 1
	v_add_f32_dpp v1, v1, v1 row_half_mirror row_mask:0xf bank_mask:0xf

; __device__ __forceinline__ int crow(int r, int hi) { return (r & 3) + 8 * (r >> 2) + 4 * hi; }
; __device__ __forceinline__ unsigned short f2bf(float f) { unsigned u = __float_as_uint(f); return (unsigned short)((u + 0x7fffu + ((u >> 16) & 1u)) >> 16); }
; __device__ __forceinline__ unsigned f2bf(float f) { unsigned u = __float_as_uint(f); return (u + 0x7fffu + ((u >> 16) & 1u)) >> 16; }
; template <bool DIFF> ...
;     ...
;       float ss = o[0][r] * o[0][r] + o[1][r] * o[1][r] + o[2][r] * o[2][r] + o[3][r] * o[3][r];
;       ss += __shfl_xor(ss, 1); ss += __shfl_xor(ss, 2); ss += __shfl_xor(ss, 4); ss += __shfl_xor(ss, 8); ss += __shfl_xor(ss, 16);
;       const float rs = 1.0f / sqrtf(ss * (1.0f / 128.0f) + 1e-6f);
;       bf16* orow = Ow + (size_t)crow(r, hi) * 2048 + r32;
; #pragma unroll
;       for (int d = 0; d < 4; ++d) orow[32 * d] = f2bf(o[d][r] * rs * gsub[d]);
	s_waitcnt lgkmcnt(0)
	s_nop 1
	v_add_f32_dpp v1, v1, v1 row_mirror row_mask:0xf bank_mask:0xf
	ds_bpermute_b32 v2, v158, v1
	s_waitcnt lgkmcnt(0)
	v_add_f32_e32 v1, v1, v2
	v_fmamk_f32 v1, v1, 0x3c000000, v160
	v_mul_f32_e32 v2, 0x4f800000, v1
	v_cmp_gt_f32_e32 vcc, s74, v1
	s_nop 1
	v_cndmask_b32_e32 v1, v1, v2, vcc
	v_sqrt_f32_e32 v4, v1
	v_add_co_u32_e64 v2, s[4:5], s84, v64
	v_add_u32_e32 v5, -1, v4
	s_nop 0
	v_addc_co_u32_e64 v3, s[4:5], 0, v65, s[4:5]
	v_add_u32_e32 v6, 1, v4
	v_fma_f32 v7, -v5, v4, v1
	v_fma_f32 v8, -v6, v4, v1
	v_cmp_ge_f32_e64 s[4:5], 0, v7
	s_nop 1
	v_cndmask_b32_e64 v4, v4, v5, s[4:5]
	v_cmp_lt_f32_e64 s[4:5], 0, v8
	s_nop 1
	v_cndmask_b32_e64 v4, v4, v6, s[4:5]
	v_mul_f32_e32 v5, 0x37800000, v4
	v_cndmask_b32_e32 v4, v4, v5, vcc
	v_cmp_class_f32_e32 vcc, v1, v161
	s_nop 1
	v_cndmask_b32_e32 v1, v4, v1, vcc
	v_div_scale_f32 v6, s[4:5], v1, v1, 1.0
	v_rcp_f32_e32 v7, v6
	v_add_co_u32_e32 v4, vcc, s85, v64
	v_fma_f32 v9, -v6, v7, 1.0
	s_nop 0
	v_addc_co_u32_e32 v5, vcc, 0, v65, vcc
	v_div_scale_f32 v8, vcc, 1.0, v1, 1.0
	v_fmac_f32_e32 v7, v9, v7
	v_mul_f32_e32 v9, v8, v7
	v_fma_f32 v10, -v6, v9, v8
	v_fmac_f32_e32 v9, v10, v7
	v_fma_f32 v6, -v6, v9, v8
	v_div_fmas_f32 v6, v6, v7, v9
	v_div_fixup_f32 v1, v6, v1, 1.0
	v_mul_f32_e32 v6, v12, v1
	v_mul_f32_e32 v7, v28, v1
	v_mul_f32_e32 v8, v44, v1
	v_mul_f32_e32 v6, v0, v6
	v_mul_f32_e32 v7, v16, v7
	v_mul_f32_e32 v8, v32, v8
	v_bfe_u32 v9, v6, 16, 1
	v_bfe_u32 v10, v7, 16, 1
	v_bfe_u32 v11, v8, 16, 1
	v_add3_u32 v6, v6, v9, s75
	v_mul_f32_e32 v1, v60, v1
	v_add3_u32 v7, v7, v10, s75
	global_store_short_d16_hi v[4:5], v6, off offset:-4096
	global_store_short_d16_hi v[2:3], v7, off offset:64
	v_add3_u32 v6, v8, v11, s75
	v_mul_f32_e32 v1, v48, v1
	global_store_short_d16_hi v[2:3], v6, off offset:128
	v_bfe_u32 v6, v1, 16, 1
	v_add3_u32 v1, v1, v6, s75
	global_store_short_d16_hi v[2:3], v1, off offset:192
	v_mul_f32_e32 v1, v29, v29
	v_fmac_f32_e32 v1, v13, v13
	v_fmac_f32_e32 v1, v45, v45
	v_fmac_f32_e32 v1, v61, v61

; template <bool DIFF> ...
;     ...
;       ss += __shfl_xor(ss, 1); ss += __shfl_xor(ss, 2); ss += __shfl_xor(ss, 4); ss += __shfl_xor(ss, 8); ss += __shfl_xor(ss, 16);
	s_waitcnt lgkmcnt(0)
	s_nop 1
	v_add_f32_dpp v1, v1, v1 quad_perm:[1,0,3,2] row_mask:0xf bank_mask:0xf

; template <bool DIFF> ...
;     ...
;       ss += __shfl_xor(ss, 1); ss += __shfl_xor(ss, 2); ss += __shfl_xor(ss, 4); ss += __shfl_xor(ss, 8); ss += __shfl_xor(ss, 16);
	s_waitcnt lgkmcnt(0)
	s_nop 1
	v_add_f32_dpp v1, v1, v1 quad_perm:[2,3,0,1] row_mask:0xf bank_mask:0xf

; template <bool DIFF> ...
;     ...
;       float ss = o[0][r] * o[0][r] + o[1][r] * o[1][r] + o[2][r] * o[2][r] + o[3][r] * o[3][r];
;       ss += __shfl_xor(ss, 1); ss += __shfl_xor(ss, 2); ss += __shfl_xor(ss, 4); ss += __shfl_xor(ss, 8); ss += __shfl_xor(ss, 16);
	s_waitcnt lgkmcnt(0)
	s_nop 1
	v_add_f32_dpp v1, v1, v1 row_half_mirror row_mask:0xf bank_mask:0xf

; __device__ __forceinline__ int crow(int r, int hi) { return (r & 3) + 8 * (r >> 2) + 4 * hi; }
; __device__ __forceinline__ unsigned short f2bf(float f) { unsigned u = __float_as_uint(f); return (unsigned short)((u + 0x7fffu + ((u >> 16) & 1u)) >> 16); }
; __device__ __forceinline__ unsigned f2bf(float f) { unsigned u = __float_as_uint(f); return (u + 0x7fffu + ((u >> 16) & 1u)) >> 16; }
; template <bool DIFF> ...
;     ...
;     for (int r = 0; r < 16; ++r) {
;       float ss = o[0][r] * o[0][r] + o[1][r] * o[1][r] + o[2][r] * o[2][r] + o[3][r] * o[3][r];
;       ss += __shfl_xor(ss, 1); ss += __shfl_xor(ss, 2); ss += __shfl_xor(ss, 4); ss += __shfl_xor(ss, 8); ss += __shfl_xor(ss, 16);
;       const float rs = 1.0f / sqrtf(ss * (1.0f / 128.0f) + 1e-6f);
;       bf16* orow = Ow + (size_t)crow(r, hi) * 2048 + r32;
; #pragma unroll
;       for (int d = 0; d < 4; ++d) orow[32 * d] = f2bf(o[d][r] * rs * gsub[d]);
	s_waitcnt lgkmcnt(0)
	s_nop 1
	v_add_f32_dpp v1, v1, v1 row_mirror row_mask:0xf bank_mask:0xf
	ds_bpermute_b32 v2, v158, v1
	s_waitcnt lgkmcnt(0)
	v_add_f32_e32 v1, v1, v2
	v_fmamk_f32 v1, v1, 0x3c000000, v160
	v_mul_f32_e32 v2, 0x4f800000, v1
	v_cmp_gt_f32_e32 vcc, s74, v1
	s_nop 1
	v_cndmask_b32_e32 v1, v1, v2, vcc
	v_sqrt_f32_e32 v2, v1
	s_nop 0
	v_add_u32_e32 v3, -1, v2
	v_add_u32_e32 v6, 1, v2
	v_fma_f32 v7, -v3, v2, v1
	v_fma_f32 v8, -v6, v2, v1
	v_cmp_ge_f32_e64 s[4:5], 0, v7
	s_nop 1
	v_cndmask_b32_e64 v2, v2, v3, s[4:5]
	v_cmp_lt_f32_e64 s[4:5], 0, v8
	s_nop 1
	v_cndmask_b32_e64 v2, v2, v6, s[4:5]
	v_mul_f32_e32 v3, 0x37800000, v2
	v_cndmask_b32_e32 v2, v2, v3, vcc
	v_cmp_class_f32_e32 vcc, v1, v161
	s_nop 1
	v_cndmask_b32_e32 v1, v2, v1, vcc
	v_div_scale_f32 v2, s[4:5], v1, v1, 1.0
	v_rcp_f32_e32 v3, v2
	v_div_scale_f32 v6, vcc, 1.0, v1, 1.0
	v_fma_f32 v7, -v2, v3, 1.0
	v_fmac_f32_e32 v3, v7, v3
	v_mul_f32_e32 v7, v6, v3
	v_fma_f32 v8, -v2, v7, v6
	v_fmac_f32_e32 v7, v8, v3
	v_fma_f32 v2, -v2, v7, v6
	v_div_fmas_f32 v2, v2, v3, v7
	v_div_fixup_f32 v1, v2, v1, 1.0
	v_mul_f32_e32 v2, v13, v1
	v_mul_f32_e32 v3, v29, v1
	v_mul_f32_e32 v6, v45, v1
	v_mul_f32_e32 v1, v61, v1
	v_mul_f32_e32 v2, v0, v2
	v_mul_f32_e32 v3, v16, v3
	v_mul_f32_e32 v6, v32, v6
	v_mul_f32_e32 v1, v48, v1
	v_bfe_u32 v7, v2, 16, 1
	v_bfe_u32 v8, v3, 16, 1
	v_bfe_u32 v9, v6, 16, 1
	v_bfe_u32 v10, v1, 16, 1
	v_add3_u32 v2, v2, v7, s75
	v_add3_u32 v3, v3, v8, s75
	v_add3_u32 v6, v6, v9, s75
	v_add3_u32 v1, v1, v10, s75
	global_store_short_d16_hi v[4:5], v2, off
	global_store_short_d16_hi v[4:5], v3, off offset:64
	global_store_short_d16_hi v[4:5], v6, off offset:128
	global_store_short_d16_hi v[4:5], v1, off offset:192
	v_mul_f32_e32 v1, v30, v30
	v_fmac_f32_e32 v1, v14, v14
	v_fmac_f32_e32 v1, v46, v46
	v_fmac_f32_e32 v1, v62, v62

; template <bool DIFF> ...
;     ...
;       float ss = o[0][r] * o[0][r] + o[1][r] * o[1][r] + o[2][r] * o[2][r] + o[3][r] * o[3][r];
;       ss += __shfl_xor(ss, 1); ss += __shfl_xor(ss, 2); ss += __shfl_xor(ss, 4); ss += __shfl_xor(ss, 8); ss += __shfl_xor(ss, 16);
	s_waitcnt lgkmcnt(0)
	s_nop 1
	v_add_f32_dpp v1, v1, v1 quad_perm:[1,0,3,2] row_mask:0xf bank_mask:0xf

; template <bool DIFF> ...
;     ...
;       float ss = o[0][r] * o[0][r] + o[1][r] * o[1][r] + o[2][r] * o[2][r] + o[3][r] * o[3][r];
;       ss += __shfl_xor(ss, 1); ss += __shfl_xor(ss, 2); ss += __shfl_xor(ss, 4); ss += __shfl_xor(ss, 8); ss += __shfl_xor(ss, 16);
	s_waitcnt lgkmcnt(0)
	s_nop 1
	v_add_f32_dpp v1, v1, v1 quad_perm:[2,3,0,1] row_mask:0xf bank_mask:0xf

; template <bool DIFF> ...
;     ...
;       float ss = o[0][r] * o[0][r] + o[1][r] * o[1][r] + o[2][r] * o[2][r] + o[3][r] * o[3][r];
;       ss += __shfl_xor(ss, 1); ss += __shfl_xor(ss, 2); ss += __shfl_xor(ss, 4); ss += __shfl_xor(ss, 8); ss += __shfl_xor(ss, 16);
	s_waitcnt lgkmcnt(0)
	s_nop 1
	v_add_f32_dpp v1, v1, v1 row_half_mirror row_mask:0xf bank_mask:0xf

; #define SBAR() __builtin_amdgcn_sched_barrier(0)
; __device__ __forceinline__ int crow(int r, int hi) { return (r & 3) + 8 * (r >> 2) + 4 * hi; }
; __device__ __forceinline__ unsigned short f2bf(float f) { unsigned u = __float_as_uint(f); return (unsigned short)((u + 0x7fffu + ((u >> 16) & 1u)) >> 16); }
; __device__ __forceinline__ unsigned f2bf(float f) { unsigned u = __float_as_uint(f); return (u + 0x7fffu + ((u >> 16) & 1u)) >> 16; }
; template <bool DIFF> ...
;     ...
;     for (int r = 0; r < 16; ++r) {
;       float ss = o[0][r] * o[0][r] + o[1][r] * o[1][r] + o[2][r] * o[2][r] + o[3][r] * o[3][r];
;       ss += __shfl_xor(ss, 1); ss += __shfl_xor(ss, 2); ss += __shfl_xor(ss, 4); ss += __shfl_xor(ss, 8); ss += __shfl_xor(ss, 16);
;       const float rs = 1.0f / sqrtf(ss * (1.0f / 128.0f) + 1e-6f);
;       bf16* orow = Ow + (size_t)crow(r, hi) * 2048 + r32;
; #pragma unroll
;       for (int d = 0; d < 4; ++d) orow[32 * d] = f2bf(o[d][r] * rs * gsub[d]);
;       asm volatile("" ::: "memory"); SBAR();
	s_waitcnt lgkmcnt(0)
	s_nop 1
	v_add_f32_dpp v1, v1, v1 row_mirror row_mask:0xf bank_mask:0xf
	ds_bpermute_b32 v2, v158, v1
	s_waitcnt lgkmcnt(0)
	v_add_f32_e32 v1, v1, v2
	v_fmamk_f32 v1, v1, 0x3c000000, v160
	v_mul_f32_e32 v2, 0x4f800000, v1
	v_cmp_gt_f32_e32 vcc, s74, v1
	s_nop 1
	v_cndmask_b32_e32 v1, v1, v2, vcc
	v_sqrt_f32_e32 v4, v1
	v_add_co_u32_e64 v2, s[4:5], s86, v64
	v_add_u32_e32 v5, -1, v4
	s_nop 0
	v_addc_co_u32_e64 v3, s[4:5], 0, v65, s[4:5]
	v_add_u32_e32 v6, 1, v4
	v_fma_f32 v7, -v5, v4, v1
	v_fma_f32 v8, -v6, v4, v1
	v_cmp_ge_f32_e64 s[4:5], 0, v7
	s_nop 1
	v_cndmask_b32_e64 v4, v4, v5, s[4:5]
	v_cmp_lt_f32_e64 s[4:5], 0, v8
	s_nop 1
	v_cndmask_b32_e64 v4, v4, v6, s[4:5]
	v_mul_f32_e32 v5, 0x37800000, v4
	v_cndmask_b32_e32 v4, v4, v5, vcc
	v_cmp_class_f32_e32 vcc, v1, v161
	s_nop 1
	v_cndmask_b32_e32 v1, v4, v1, vcc
	v_div_scale_f32 v6, s[4:5], v1, v1, 1.0
	v_rcp_f32_e32 v7, v6
	v_add_co_u32_e32 v4, vcc, s87, v64
	v_fma_f32 v9, -v6, v7, 1.0
	s_nop 0
	v_addc_co_u32_e32 v5, vcc, 0, v65, vcc
	v_div_scale_f32 v8, vcc, 1.0, v1, 1.0
	v_fmac_f32_e32 v7, v9, v7
	v_mul_f32_e32 v9, v8, v7
	v_fma_f32 v10, -v6, v9, v8
	v_fmac_f32_e32 v9, v10, v7
	v_fma_f32 v6, -v6, v9, v8
	v_div_fmas_f32 v6, v6, v7, v9
	v_div_fixup_f32 v1, v6, v1, 1.0
	v_mul_f32_e32 v6, v14, v1
	v_mul_f32_e32 v7, v30, v1
	v_mul_f32_e32 v8, v46, v1
	v_mul_f32_e32 v6, v0, v6
	v_mul_f32_e32 v7, v16, v7
	v_mul_f32_e32 v8, v32, v8
	v_bfe_u32 v9, v6, 16, 1
	v_bfe_u32 v10, v7, 16, 1
	v_bfe_u32 v11, v8, 16, 1
	v_add3_u32 v6, v6, v9, s75
	v_mul_f32_e32 v1, v62, v1
	v_add3_u32 v7, v7, v10, s75
	global_store_short_d16_hi v[4:5], v6, off offset:-4096
	global_store_short_d16_hi v[2:3], v7, off offset:64
	v_add3_u32 v6, v8, v11, s75
	v_mul_f32_e32 v1, v48, v1
	global_store_short_d16_hi v[2:3], v6, off offset:128
	v_bfe_u32 v6, v1, 16, 1
	v_add3_u32 v1, v1, v6, s75
	global_store_short_d16_hi v[2:3], v1, off offset:192
	v_mul_f32_e32 v1, v31, v31
	v_fmac_f32_e32 v1, v15, v15
	v_fmac_f32_e32 v1, v47, v47
	v_fmac_f32_e32 v1, v63, v63

; template <bool DIFF> ...
;     ...
;       float ss = o[0][r] * o[0][r] + o[1][r] * o[1][r] + o[2][r] * o[2][r] + o[3][r] * o[3][r];
;       ss += __shfl_xor(ss, 1); ss += __shfl_xor(ss, 2); ss += __shfl_xor(ss, 4); ss += __shfl_xor(ss, 8); ss += __shfl_xor(ss, 16);
	s_waitcnt lgkmcnt(0)
	s_nop 1
	v_add_f32_dpp v1, v1, v1 quad_perm:[1,0,3,2] row_mask:0xf bank_mask:0xf

; template <bool DIFF> ...
;     ...
;       float ss = o[0][r] * o[0][r] + o[1][r] * o[1][r] + o[2][r] * o[2][r] + o[3][r] * o[3][r];
;       ss += __shfl_xor(ss, 1); ss += __shfl_xor(ss, 2); ss += __shfl_xor(ss, 4); ss += __shfl_xor(ss, 8); ss += __shfl_xor(ss, 16);
	s_waitcnt lgkmcnt(0)
	s_nop 1
	v_add_f32_dpp v1, v1, v1 quad_perm:[2,3,0,1] row_mask:0xf bank_mask:0xf

; template <bool DIFF> ...
;     ...
;       float ss = o[0][r] * o[0][r] + o[1][r] * o[1][r] + o[2][r] * o[2][r] + o[3][r] * o[3][r];
;       ss += __shfl_xor(ss, 1); ss += __shfl_xor(ss, 2); ss += __shfl_xor(ss, 4); ss += __shfl_xor(ss, 8); ss += __shfl_xor(ss, 16);
	s_waitcnt lgkmcnt(0)
	s_nop 1
	v_add_f32_dpp v1, v1, v1 row_half_mirror row_mask:0xf bank_mask:0xf

; #define SBAR() __builtin_amdgcn_sched_barrier(0)
; __device__ __forceinline__ int crow(int r, int hi) { return (r & 3) + 8 * (r >> 2) + 4 * hi; }
; __device__ __forceinline__ unsigned short f2bf(float f) { unsigned u = __float_as_uint(f); return (unsigned short)((u + 0x7fffu + ((u >> 16) & 1u)) >> 16); }
; __device__ __forceinline__ unsigned f2bf(float f) { unsigned u = __float_as_uint(f); return (u + 0x7fffu + ((u >> 16) & 1u)) >> 16; }
; #define AIN(i) ((const float*)ldarg(i))
; #define G lgrid()
; template <bool DIFF> ...
;     ...
;     for (int r = 0; r < 16; ++r) {
;       float ss = o[0][r] * o[0][r] + o[1][r] * o[1][r] + o[2][r] * o[2][r] + o[3][r] * o[3][r];
;       ss += __shfl_xor(ss, 1); ss += __shfl_xor(ss, 2); ss += __shfl_xor(ss, 4); ss += __shfl_xor(ss, 8); ss += __shfl_xor(ss, 16);
;       const float rs = 1.0f / sqrtf(ss * (1.0f / 128.0f) + 1e-6f);
;       bf16* orow = Ow + (size_t)crow(r, hi) * 2048 + r32;
; #pragma unroll
;       for (int d = 0; d < 4; ++d) orow[32 * d] = f2bf(o[d][r] * rs * gsub[d]);
;       asm volatile("" ::: "memory"); SBAR();
;     }
; __global__ void __launch_bounds__(NTHR, 2) mega_fwd(Args a_unused) {
;     ...
;     for (int u = vcu; u < 1536; u += G) {
;       int s, h, qb, L;
;       if (u < 1024) { qb = u & 15; const int bh = u >> 4; h = bh & 7; s = 8 + (bh >> 3); L = 4096; }
;       else { const int v = u - 1024; qb = v & 7; const int bh = v >> 3; h = bh & 7; s = bh >> 3; L = 2048; }
;       const size_t mbase = s < 8 ? (size_t)s * 2048 : (size_t)TP + (size_t)(s - 8) * 4096;
;       att::attn_unit<true>(QA + (mbase + 256 * qb) * 1024 + 128 * h, KA + mbase * 1024 + 128 * h, VA + mbase * 1024 + 128 * h,
;                            O + (mbase + 256 * qb) * 2048 + 128 * h, 0, L / 64, 256 * qb, 0, lam, AIN(4), h, AIN(12), (char*)lds);
;     }
	s_waitcnt lgkmcnt(0)
	s_nop 1
	v_add_f32_dpp v1, v1, v1 row_mirror row_mask:0xf bank_mask:0xf
	ds_bpermute_b32 v2, v158, v1
	s_waitcnt lgkmcnt(0)
	v_add_f32_e32 v1, v1, v2
	v_fmamk_f32 v1, v1, 0x3c000000, v160
	v_mul_f32_e32 v2, 0x4f800000, v1
	v_cmp_gt_f32_e32 vcc, s74, v1
	s_nop 1
	v_cndmask_b32_e32 v1, v1, v2, vcc
	v_sqrt_f32_e32 v2, v1
	s_nop 0
	v_add_u32_e32 v3, -1, v2
	v_add_u32_e32 v6, 1, v2
	v_fma_f32 v7, -v3, v2, v1
	v_fma_f32 v8, -v6, v2, v1
	v_cmp_ge_f32_e64 s[4:5], 0, v7
	s_nop 1
	v_cndmask_b32_e64 v2, v2, v3, s[4:5]
	v_cmp_lt_f32_e64 s[4:5], 0, v8
	s_nop 1
	v_cndmask_b32_e64 v2, v2, v6, s[4:5]
	v_mul_f32_e32 v3, 0x37800000, v2
	v_cndmask_b32_e32 v2, v2, v3, vcc
	v_cmp_class_f32_e32 vcc, v1, v161
	s_nop 1
	v_cndmask_b32_e32 v1, v2, v1, vcc
	v_div_scale_f32 v2, s[4:5], v1, v1, 1.0
	v_rcp_f32_e32 v3, v2
	v_div_scale_f32 v6, vcc, 1.0, v1, 1.0
	v_fma_f32 v7, -v2, v3, 1.0
	v_fmac_f32_e32 v3, v7, v3
	v_mul_f32_e32 v7, v6, v3
	v_fma_f32 v8, -v2, v7, v6
	v_fmac_f32_e32 v7, v8, v3
	v_fma_f32 v2, -v2, v7, v6
	v_div_fmas_f32 v2, v2, v3, v7
	v_div_fixup_f32 v1, v2, v1, 1.0
	v_mul_f32_e32 v2, v15, v1
	v_mul_f32_e32 v3, v31, v1
	v_mul_f32_e32 v6, v47, v1
	v_mul_f32_e32 v1, v63, v1
	v_mul_f32_e32 v0, v0, v2
	v_mul_f32_e32 v2, v16, v3
	v_mul_f32_e32 v3, v32, v6
	v_mul_f32_e32 v1, v48, v1
	v_bfe_u32 v6, v0, 16, 1
	v_bfe_u32 v7, v2, 16, 1
	v_bfe_u32 v8, v3, 16, 1
	v_bfe_u32 v9, v1, 16, 1
	v_add3_u32 v0, v0, v6, s75
	v_add3_u32 v2, v2, v7, s75
	v_add3_u32 v3, v3, v8, s75
	v_add3_u32 v1, v1, v9, s75
	global_store_short_d16_hi v[4:5], v0, off
	global_store_short_d16_hi v[4:5], v2, off offset:64
	global_store_short_d16_hi v[4:5], v3, off offset:128
	global_store_short_d16_hi v[4:5], v1, off offset:192
	s_load_dwordx2 s[4:5], s[0:1], 0x100
	s_waitcnt lgkmcnt(0)
	s_mov_b32 s2, s4
	s_add_i32 s88, s2, s88
	s_cmpk_lt_i32 s88, 0x600
	s_cbranch_scc0 .LBB0_345
